# RG-LRU tile passes: x rows of the next tile loaded one job ahead (no exposed load latency at the start of each tile), job-end wait only on LDS
# baseline (speedup 1.0000x reference)
; template <int PASS>
; __device__ __forceinline__ void lru_tile_phase(const Params& p, int jl, int Mrows, char* smem, int tid, int bid) {
;     ...
;   for (int job = bid; job < ntt * 8; job += gridDim.x) {
;     asm volatile("" : "+v"(tid));
;     const int lane = tid & 63, wid = tid >> 6, l32 = lane & 31, hi = lane >> 5;
;     const int tt = job >> 3, n = job & 7;
;     const bool lat = tt < 512;
;     const int rowbase = lat ? tt * 64 : ML + (tt - 512) * 64;
;     const int sloc = lat ? (tt & 63) * 64 : ((tt - 512) & 3) * 64;
;     const int TT = lat ? SEQL : CTXL;
;     unsigned gv[16]; float carry_in = 0.f;
;     if (PASS == 2) {
;       const int ch = tid & 127, tg = tid >> 7;
; #pragma unroll
;       for (int i = 0; i < 16; ++i) gv[i] = P2[(size_t)(rowbase + tg * 16 + i) * 2048 + n * 128 + ch];
;       if (tid < 256) carry_in = carry[(size_t)(tt * 2 + (tid >> 7)) * 1024 + n * 128 + (tid & 127)];
;     }
;     {
;       const int ch = tid & 127, tg = tid >> 7, t0 = tg * 16;
;       const int col = n * 128 + ch;
;       float cw0 = p.in[18][(size_t)(jl * 4 + 0) * 1024 + col], cw1 = p.in[18][(size_t)(jl * 4 + 1) * 1024 + col];
;       float cw2 = p.in[18][(size_t)(jl * 4 + 2) * 1024 + col], cw3 = p.in[18][(size_t)(jl * 4 + 3) * 1024 + col];
;       const float cb = p.in[19][(size_t)jl * 1024 + col];
;       float xb[19]; unsigned xraw[19];
;       const u16* xsrc = P2 + (size_t)(rowbase - sloc) * 2048 + 1024 + col;
; #pragma unroll
;       for (int i = 0; i < 19; ++i) {
;         const int s = sloc + t0 + i - 2;
;         const int sc = s < 0 ? 0 : (s >= TT ? TT - 1 : s);
;         xraw[i] = xsrc[(size_t)sc * 2048];
;       }
.LBB0_216:
	s_andn2_b64 vcc, exec, s[0:1]
	s_cbranch_vccnz .LBB0_229
	s_lshr_b32 s26, s34, 3
	s_cmp_ge_i32 s62, s26
	s_cbranch_scc1 .LBB0_229
	v_readlane_b32 s0, v253, 1
	v_readlane_b32 s1, v253, 2
	s_sub_u32 s0, s0, 0x138
	s_subb_u32 s1, s1, 0
	s_load_dwordx4 s[36:39], s[0:1], 0x90
	s_load_dwordx2 s[40:41], s[0:1], 0xa8
	s_load_dwordx2 s[44:45], s[0:1], 0xb8
	s_load_dwordx2 s[46:47], s[0:1], 0xc0
	s_load_dwordx2 s[42:43], s[0:1], 0xd0
	s_load_dwordx4 s[48:51], s[0:1], 0xe0
	s_load_dwordx2 s[4:5], s[0:1], 0x128
	s_waitcnt lgkmcnt(0)
	s_lshl_b32 s0, s72, 14
	s_add_u32 s36, s36, s0
	s_addc_u32 s37, s37, 0
	s_lshl_b32 s0, s72, 12
	s_add_u32 s38, s38, s0
	s_addc_u32 s39, s39, 0
	s_add_u32 s40, s40, s0
	s_addc_u32 s41, s41, 0
	s_add_u32 s42, s42, s0
	s_addc_u32 s43, s43, 0
	s_add_u32 s44, s44, s0
	s_addc_u32 s45, s45, 0
	s_add_u32 s46, s46, s0
	s_addc_u32 s47, s47, 0
	s_add_u32 s48, s48, s0
	s_addc_u32 s49, s49, 0
	s_add_u32 s50, s50, s0
	s_addc_u32 s51, s51, 0
	s_add_u32 s22, s4, 0x129dc000
	s_addc_u32 s23, s5, 0
	s_add_u32 s24, s4, 0x1325c000
	s_addc_u32 s25, s5, 0
	s_add_u32 s28, s4, 0x1369c000
	s_addc_u32 s29, s5, 0
	s_add_u32 s18, s4, 0x8e00000
	s_addc_u32 s19, s5, 0
	v_and_b32_e32 v80, 63, v203
	v_lshrrev_b32_e32 v81, 6, v203
	v_and_b32_e32 v236, 31, v203
	v_bfe_u32 v237, v203, 5, 1
	v_lshrrev_b32_e32 v84, 4, v203
	v_and_b32_e32 v99, 15, v203
	v_readfirstlane_b32 s0, v81
	s_and_b32 s1, s0, 3
	s_lshr_b32 s16, s0, 2
	s_mov_b32 s27, s0
	v_lshlrev_b32_e32 v190, 1, v84
	v_lshlrev_b32_e32 v191, 4, v99
	v_or_b32_e32 v195, 0, v190
	v_and_b32_e32 v196, 15, v195
	v_xor_b32_e32 v196, v99, v196
	v_lshlrev_b32_e32 v196, 4, v196
	v_lshl_or_b32 v183, v195, 8, v196
	v_or_b32_e32 v195, 1, v190
	v_and_b32_e32 v196, 15, v195
	v_xor_b32_e32 v196, v99, v196
	v_lshlrev_b32_e32 v196, 4, v196
	v_lshl_or_b32 v184, v195, 8, v196
	v_and_b32_e32 v195, 15, v236
	v_xor_b32_e32 v195, v237, v195
	v_lshlrev_b32_e32 v195, 4, v195
	v_lshl_or_b32 v185, v236, 8, v195
	s_lshl_b32 s4, s1, 5
	v_add_u32_e32 v195, s4, v236
	s_lshl_b32 s5, s16, 6
	v_lshl_add_u32 v196, v237, 2, s5
	v_lshlrev_b32_e32 v196, 7, v196
	v_add_u32_e32 v196, v196, v195
	v_lshlrev_b32_e32 v186, 2, v196
	v_add_u32_e32 v186, 0x4000, v186
	v_add_u32_e32 v187, 0x10000, v186
	v_bfe_u32 v196, v236, 3, 1
	v_cmp_eq_u32_e32 vcc, v196, v237
	v_and_b32_e32 v197, 7, v236
	v_lshrrev_b32_e32 v198, 1, v197
	v_and_b32_e32 v197, 1, v197
	v_lshlrev_b32_e32 v197, 4, v197
	v_mov_b32_e32 v199, 0x3f80
	v_lshlrev_b32_e32 v199, v197, v199
	v_cndmask_b32_e32 v199, 0, v199, vcc
	v_lshrrev_b32_e32 v200, 4, v236
	v_cmp_eq_u32_e32 vcc, 0, v200
	v_cmp_eq_u32_e64 s[4:5], 0, v198
	s_and_b64 vcc, vcc, s[4:5]
	v_cndmask_b32_e32 v172, 0, v199, vcc
	v_cmp_eq_u32_e32 vcc, 0, v200
	v_cmp_eq_u32_e64 s[4:5], 1, v198
	s_and_b64 vcc, vcc, s[4:5]
	v_cndmask_b32_e32 v173, 0, v199, vcc
	v_cmp_eq_u32_e32 vcc, 0, v200
	v_cmp_eq_u32_e64 s[4:5], 2, v198
	s_and_b64 vcc, vcc, s[4:5]
	v_cndmask_b32_e32 v174, 0, v199, vcc
	v_cmp_eq_u32_e32 vcc, 0, v200
	v_cmp_eq_u32_e64 s[4:5], 3, v198
	s_and_b64 vcc, vcc, s[4:5]
	v_cndmask_b32_e32 v175, 0, v199, vcc
	v_cmp_eq_u32_e32 vcc, 1, v200
	v_cmp_eq_u32_e64 s[4:5], 0, v198
	s_and_b64 vcc, vcc, s[4:5]
	v_cndmask_b32_e32 v176, 0, v199, vcc
	v_cmp_eq_u32_e32 vcc, 1, v200
	v_cmp_eq_u32_e64 s[4:5], 1, v198
	s_and_b64 vcc, vcc, s[4:5]
	v_cndmask_b32_e32 v177, 0, v199, vcc
	v_cmp_eq_u32_e32 vcc, 1, v200
	v_cmp_eq_u32_e64 s[4:5], 2, v198
	s_and_b64 vcc, vcc, s[4:5]
	v_cndmask_b32_e32 v178, 0, v199, vcc
	v_cmp_eq_u32_e32 vcc, 1, v200
	v_cmp_eq_u32_e64 s[4:5], 3, v198
	s_and_b64 vcc, vcc, s[4:5]
	v_cndmask_b32_e32 v179, 0, v199, vcc
	v_and_b32_e32 v195, 0x7f, v203
	v_bfe_u32 v196, v203, 7, 1
	v_lshl_or_b32 v196, v196, 13, v195
	v_lshlrev_b32_e32 v188, 2, v196
	v_add_u32_e32 v188, 0x4000, v188
	v_bfe_u32 v196, v203, 7, 1
	v_lshl_or_b32 v194, v196, 10, v195
	v_lshrrev_b32_e32 v195, 3, v203
	v_and_b32_e32 v196, 7, v203
	v_lshlrev_b32_e32 v197, 5, v196
	v_lshl_or_b32 v192, v195, 12, v197
	v_lshl_or_b32 v193, v195, 11, v197
	v_lshlrev_b32_e32 v197, 6, v196
	v_lshl_or_b32 v189, v195, 9, v197
	v_add_u32_e32 v189, 0x14000, v189
	v_mov_b32_e32 v91, 0xbfb8aa3b
	s_mov_b32 s6, s62
	s_lshr_b32 s10, s6, 3
	s_and_b32 s11, s6, 7
	s_movk_i32 s0, 0x1000
	s_cmp_lt_u32 s10, 512
	s_cselect_b32 s4, 0, 512
	s_cselect_b32 s5, 0, 0x8000
	s_cselect_b32 s1, 63, 3
	s_cselect_b32 s21, s0, 0x100
	s_sub_u32 s0, s10, s4
	s_lshl_b32 s20, s0, 6
	s_add_u32 s20, s20, s5
	s_and_b32 s10, s0, s1
	s_lshl_b32 s10, s10, 6
	s_cmp_eq_u32 s10, 0
	s_cselect_b32 s4, 0, -2
	s_add_u32 s0, s10, 64
	s_cmp_eq_u32 s0, s21
	s_cselect_b32 s5, 63, 0x41
	s_lshl_b32 s0, s20, 12
	s_lshl_b32 s1, s11, 8
	s_add_u32 s0, s0, s1
	s_add_u32 s0, s92, s0
	s_addc_u32 s1, s93, 0
	s_sub_u32 s0, s0, 0x1800
	s_subb_u32 s1, s1, 0
	v_add_u32_e32 v44, -2, v190
	v_max_i32_e32 v49, s4, v44
	v_min_i32_e32 v49, s5, v49
	v_add_u32_e32 v195, 2, v49
	v_lshl_add_u32 v195, v195, 12, v191
	global_load_dwordx4 v[56:59], v195, s[0:1]
	v_add_u32_e32 v45, -1, v190
	v_max_i32_e32 v50, s4, v45
	v_min_i32_e32 v50, s5, v50
	v_add_u32_e32 v195, 2, v50
	v_lshl_add_u32 v195, v195, 12, v191
	global_load_dwordx4 v[60:63], v195, s[0:1]
	v_add_u32_e32 v46, 0, v190
	v_max_i32_e32 v51, s4, v46
	v_min_i32_e32 v51, s5, v51
	v_add_u32_e32 v195, 2, v51
	v_lshl_add_u32 v195, v195, 12, v191
	global_load_dwordx4 v[64:67], v195, s[0:1]
	v_add_u32_e32 v47, 1, v190
	v_max_i32_e32 v52, s4, v47
	v_min_i32_e32 v52, s5, v52
	v_add_u32_e32 v195, 2, v52
	v_lshl_add_u32 v195, v195, 12, v191
	global_load_dwordx4 v[68:71], v195, s[0:1]
	v_add_u32_e32 v48, 2, v190
	v_max_i32_e32 v53, s4, v48
	v_min_i32_e32 v53, s5, v53
	v_add_u32_e32 v195, 2, v53
	v_lshl_add_u32 v195, v195, 12, v191
	global_load_dwordx4 v[72:75], v195, s[0:1]
	s_mov_b32 s30, -1

; __device__ __forceinline__ u16 f2bf(float x) { return (u16)(cvtpk(x, 0.f) & 0xffffu); }
; template <int PASS>
; __device__ __forceinline__ void lru_tile_phase(const Params& p, int jl, int Mrows, char* smem, int tid, int bid) {
;     ...
;     if (PASS == 2) {
;       const int ch = tid & 127, tg = tid >> 7;
; #pragma unroll
;       for (int i = 0; i < 16; ++i) gv[i] = P2[(size_t)(rowbase + tg * 16 + i) * 2048 + n * 128 + ch];
;       if (tid < 256) carry_in = carry[(size_t)(tt * 2 + (tid >> 7)) * 1024 + n * 128 + (tid & 127)];
;     }
;     {
;       const int ch = tid & 127, tg = tid >> 7, t0 = tg * 16;
;       const int col = n * 128 + ch;
;       float cw0 = p.in[18][(size_t)(jl * 4 + 0) * 1024 + col], cw1 = p.in[18][(size_t)(jl * 4 + 1) * 1024 + col];
;       float cw2 = p.in[18][(size_t)(jl * 4 + 2) * 1024 + col], cw3 = p.in[18][(size_t)(jl * 4 + 3) * 1024 + col];
;       const float cb = p.in[19][(size_t)jl * 1024 + col];
;       float xb[19]; unsigned xraw[19];
;       const u16* xsrc = P2 + (size_t)(rowbase - sloc) * 2048 + 1024 + col;
; #pragma unroll
;       for (int i = 0; i < 19; ++i) {
;         const int s = sloc + t0 + i - 2;
;         const int sc = s < 0 ? 0 : (s >= TT ? TT - 1 : s);
;         xraw[i] = xsrc[(size_t)sc * 2048];
;       }
; #pragma unroll
;       for (int i = 0; i < 19; ++i) {
;         const int s = sloc + t0 + i - 2;
;         xb[i] = (s >= 0 && s < TT) ? __uint_as_float(xraw[i] << 16) : 0.f;
;       }
; #pragma unroll
;       for (int i = 0; i < 16; ++i) {
;         const float xc = cb + cw0 * xb[i] + cw1 * xb[i + 1] + cw2 * xb[i + 2] + cw3 * xb[i + 3];
;         *(u16*)(xcL + swz256(t0 + i, ch >> 3) + (ch & 7) * 2) = f2bf(xc);
;       }
;     }
;     __syncthreads();
.Llru2_nloaded:
	s_movk_i32 s0, 0x1000
	s_cmp_lt_u32 s8, 512
	s_cselect_b32 s4, 0, 512
	s_cselect_b32 s5, 0, 0x8000
	s_cselect_b32 s1, 63, 3
	s_cselect_b32 s11, s0, 0x100
	s_sub_u32 s0, s8, s4
	s_lshl_b32 s9, s0, 6
	s_add_u32 s9, s9, s5
	s_and_b32 s10, s0, s1
	s_lshl_b32 s10, s10, 6
	s_cmp_eq_u32 s10, 0
	s_cselect_b32 s4, 0, -2
	s_add_u32 s0, s10, 64
	s_cmp_eq_u32 s0, s11
	s_cselect_b32 s5, 63, 0x41
	s_lshl_b32 s0, s9, 12
	s_lshl_b32 s1, s7, 8
	s_add_u32 s0, s0, s1
	s_add_u32 s20, s92, s0
	s_addc_u32 s21, s93, 0
	s_sub_u32 s0, s20, 0x1800
	s_subb_u32 s1, s21, 0
	global_load_dwordx4 v[92:95], v192, s[20:21]
	global_load_dwordx4 v[244:247], v192, s[20:21] offset:16
	s_lshl_b32 s0, s8, 11
	s_lshl_b32 s1, s7, 7
	s_add_u32 s0, s0, s1
	s_lshl_b32 s0, s0, 2
	s_add_u32 s0, s24, s0
	s_addc_u32 s1, s25, 0
	v_lshlrev_b32_e32 v196, 2, v194
	global_load_dword v252, v196, s[0:1]
	v_mov_b32_e32 v20, v132
	v_mov_b32_e32 v21, v133
	v_mov_b32_e32 v22, v134
	v_mov_b32_e32 v23, v135
	v_mov_b32_e32 v24, v136
	v_mov_b32_e32 v25, v137
	v_mov_b32_e32 v26, v138
	v_mov_b32_e32 v27, v139
	v_mov_b32_e32 v28, v132
	v_mov_b32_e32 v29, v133
	v_mov_b32_e32 v30, v134
	v_mov_b32_e32 v31, v135
	v_mov_b32_e32 v32, v136
	v_mov_b32_e32 v33, v137
	v_mov_b32_e32 v34, v138
	v_mov_b32_e32 v35, v139
	s_waitcnt vmcnt(9)
	v_cmp_eq_u32_e32 vcc, v44, v49
	s_nop 1
	v_cndmask_b32_e32 v56, 0, v56, vcc
	v_cndmask_b32_e32 v57, 0, v57, vcc
	v_cndmask_b32_e32 v58, 0, v58, vcc
	v_cndmask_b32_e32 v59, 0, v59, vcc
	v_lshlrev_b32_e32 v36, 16, v56
	v_and_b32_e32 v37, 0xffff0000, v56
	v_lshlrev_b32_e32 v38, 16, v57
	v_and_b32_e32 v39, 0xffff0000, v57
	v_lshlrev_b32_e32 v40, 16, v58
	v_and_b32_e32 v41, 0xffff0000, v58
	v_lshlrev_b32_e32 v42, 16, v59
	v_and_b32_e32 v43, 0xffff0000, v59
	v_fmac_f32_e32 v20, v100, v36
	v_fmac_f32_e32 v21, v101, v37
	v_fmac_f32_e32 v22, v102, v38
	v_fmac_f32_e32 v23, v103, v39
	v_fmac_f32_e32 v24, v104, v40
	v_fmac_f32_e32 v25, v105, v41
	v_fmac_f32_e32 v26, v106, v42
	v_fmac_f32_e32 v27, v107, v43
	s_waitcnt vmcnt(8)
	v_cmp_eq_u32_e32 vcc, v45, v50
	s_nop 1
	v_cndmask_b32_e32 v60, 0, v60, vcc
	v_cndmask_b32_e32 v61, 0, v61, vcc
	v_cndmask_b32_e32 v62, 0, v62, vcc
	v_cndmask_b32_e32 v63, 0, v63, vcc
	v_lshlrev_b32_e32 v36, 16, v60
	v_and_b32_e32 v37, 0xffff0000, v60
	v_lshlrev_b32_e32 v38, 16, v61
	v_and_b32_e32 v39, 0xffff0000, v61
	v_lshlrev_b32_e32 v40, 16, v62
	v_and_b32_e32 v41, 0xffff0000, v62
	v_lshlrev_b32_e32 v42, 16, v63
	v_and_b32_e32 v43, 0xffff0000, v63
	v_fmac_f32_e32 v20, v108, v36
	v_fmac_f32_e32 v21, v109, v37
	v_fmac_f32_e32 v22, v110, v38
	v_fmac_f32_e32 v23, v111, v39
	v_fmac_f32_e32 v24, v112, v40
	v_fmac_f32_e32 v25, v113, v41
	v_fmac_f32_e32 v26, v114, v42
	v_fmac_f32_e32 v27, v115, v43
	v_fmac_f32_e32 v28, v100, v36
	v_fmac_f32_e32 v29, v101, v37
	v_fmac_f32_e32 v30, v102, v38
	v_fmac_f32_e32 v31, v103, v39
	v_fmac_f32_e32 v32, v104, v40
	v_fmac_f32_e32 v33, v105, v41
	v_fmac_f32_e32 v34, v106, v42
	v_fmac_f32_e32 v35, v107, v43
	s_waitcnt vmcnt(7)
	v_cmp_eq_u32_e32 vcc, v46, v51
	s_nop 1
	v_cndmask_b32_e32 v64, 0, v64, vcc
	v_cndmask_b32_e32 v65, 0, v65, vcc
	v_cndmask_b32_e32 v66, 0, v66, vcc
	v_cndmask_b32_e32 v67, 0, v67, vcc
	v_lshlrev_b32_e32 v36, 16, v64
	v_and_b32_e32 v37, 0xffff0000, v64
	v_lshlrev_b32_e32 v38, 16, v65
	v_and_b32_e32 v39, 0xffff0000, v65
	v_lshlrev_b32_e32 v40, 16, v66
	v_and_b32_e32 v41, 0xffff0000, v66
	v_lshlrev_b32_e32 v42, 16, v67
	v_and_b32_e32 v43, 0xffff0000, v67
	v_fmac_f32_e32 v20, v116, v36
	v_fmac_f32_e32 v21, v117, v37
	v_fmac_f32_e32 v22, v118, v38
	v_fmac_f32_e32 v23, v119, v39
	v_fmac_f32_e32 v24, v120, v40
	v_fmac_f32_e32 v25, v121, v41
	v_fmac_f32_e32 v26, v122, v42
	v_fmac_f32_e32 v27, v123, v43
	v_fmac_f32_e32 v28, v108, v36
	v_fmac_f32_e32 v29, v109, v37
	v_fmac_f32_e32 v30, v110, v38
	v_fmac_f32_e32 v31, v111, v39
	v_fmac_f32_e32 v32, v112, v40
	v_fmac_f32_e32 v33, v113, v41
	v_fmac_f32_e32 v34, v114, v42
	v_fmac_f32_e32 v35, v115, v43
	s_waitcnt vmcnt(6)
	v_cmp_eq_u32_e32 vcc, v47, v52
	s_nop 1
	v_cndmask_b32_e32 v68, 0, v68, vcc
	v_cndmask_b32_e32 v69, 0, v69, vcc
	v_cndmask_b32_e32 v70, 0, v70, vcc
	v_cndmask_b32_e32 v71, 0, v71, vcc
	v_lshlrev_b32_e32 v36, 16, v68
	v_and_b32_e32 v37, 0xffff0000, v68
	v_lshlrev_b32_e32 v38, 16, v69
	v_and_b32_e32 v39, 0xffff0000, v69
	v_lshlrev_b32_e32 v40, 16, v70
	v_and_b32_e32 v41, 0xffff0000, v70
	v_lshlrev_b32_e32 v42, 16, v71
	v_and_b32_e32 v43, 0xffff0000, v71
	v_fmac_f32_e32 v20, v124, v36
	v_fmac_f32_e32 v21, v125, v37
	v_fmac_f32_e32 v22, v126, v38
	v_fmac_f32_e32 v23, v127, v39
	v_fmac_f32_e32 v24, v128, v40
	v_fmac_f32_e32 v25, v129, v41
	v_fmac_f32_e32 v26, v130, v42
	v_fmac_f32_e32 v27, v131, v43
	v_fmac_f32_e32 v28, v116, v36
	v_fmac_f32_e32 v29, v117, v37
	v_fmac_f32_e32 v30, v118, v38
	v_fmac_f32_e32 v31, v119, v39
	v_fmac_f32_e32 v32, v120, v40
	v_fmac_f32_e32 v33, v121, v41
	v_fmac_f32_e32 v34, v122, v42
	v_fmac_f32_e32 v35, v123, v43
	s_waitcnt vmcnt(5)
	v_cmp_eq_u32_e32 vcc, v48, v53
	s_nop 1
	v_cndmask_b32_e32 v72, 0, v72, vcc
	v_cndmask_b32_e32 v73, 0, v73, vcc
	v_cndmask_b32_e32 v74, 0, v74, vcc
	v_cndmask_b32_e32 v75, 0, v75, vcc
	v_lshlrev_b32_e32 v36, 16, v72
	v_and_b32_e32 v37, 0xffff0000, v72
	v_lshlrev_b32_e32 v38, 16, v73
	v_and_b32_e32 v39, 0xffff0000, v73
	v_lshlrev_b32_e32 v40, 16, v74
	v_and_b32_e32 v41, 0xffff0000, v74
	v_lshlrev_b32_e32 v42, 16, v75
	v_and_b32_e32 v43, 0xffff0000, v75
	v_fmac_f32_e32 v28, v124, v36
	v_fmac_f32_e32 v29, v125, v37
	v_fmac_f32_e32 v30, v126, v38
	v_fmac_f32_e32 v31, v127, v39
	v_fmac_f32_e32 v32, v128, v40
	v_fmac_f32_e32 v33, v129, v41
	v_fmac_f32_e32 v34, v130, v42
	v_fmac_f32_e32 v35, v131, v43
	v_cvt_pk_bf16_f32 v36, v20, v21
	v_cvt_pk_bf16_f32 v37, v22, v23
	v_cvt_pk_bf16_f32 v38, v24, v25
	v_cvt_pk_bf16_f32 v39, v26, v27
	v_cvt_pk_bf16_f32 v40, v28, v29
	v_cvt_pk_bf16_f32 v41, v30, v31
	v_cvt_pk_bf16_f32 v42, v32, v33
	v_cvt_pk_bf16_f32 v43, v34, v35
	ds_write_b128 v183, v[36:39]
	ds_write_b128 v184, v[40:43]
	s_waitcnt lgkmcnt(0)
	s_barrier
; __device__ __forceinline__ float bf2f(u16 x) { return __uint_as_float(((unsigned)x) << 16); }
; __device__ __forceinline__ int crow(int r, int hi) { return (r & 3) + 8 * (r >> 2) + 4 * hi; }
; template <int PASS>
; __device__ __forceinline__ void lru_tile_phase(const Params& p, int jl, int Mrows, char* smem, int tid, int bid) {
;     ...
; #pragma unroll
;       for (int tb = 0; tb < 2; ++tb) {
;         f32x16 acc0, acc1;
; #pragma unroll
;         for (int r = 0; r < 16; ++r) { acc0[r] = 0.f; acc1[r] = 0.f; }
;         bf16x8 af[8];
; #pragma unroll
;         for (int k16 = 0; k16 < 8; ++k16) af[k16] = *(const bf16x8*)(xcL + swz256(tb * 32 + l32, k16 * 2 + hi));
; #pragma unroll
;         for (int k16 = 0; k16 < 8; ++k16) {
;           acc0 = __builtin_amdgcn_mfma_f32_32x32x16_bf16(af[k16], wb0[k16], acc0, 0, 0, 0);
;           acc1 = __builtin_amdgcn_mfma_f32_32x32x16_bf16(af[k16], wb1[k16], acc1, 0, 0, 0);
;         }
; #pragma unroll
;         for (int r = 0; r < 16; ++r) {
;           const int tok = tb * 32 + crow(r, hi);
;           const float xc = bf2f(*(const u16*)(xcL + swz256(tok, chl >> 3) + (chl & 7) * 2));
	ds_read_b128 v[48:51], v185 offset:0
	v_xor_b32_e32 v196, 32, v185
	ds_read_b128 v[52:55], v196 offset:0
	v_xor_b32_e32 v195, 64, v185
	ds_read_b128 v[56:59], v195 offset:0
	v_xor_b32_e32 v196, 96, v185
	ds_read_b128 v[60:63], v196 offset:0
	v_xor_b32_e32 v195, 128, v185
	ds_read_b128 v[64:67], v195 offset:0
	v_xor_b32_e32 v196, 160, v185
	ds_read_b128 v[68:71], v196 offset:0
	v_xor_b32_e32 v195, 192, v185
	ds_read_b128 v[72:75], v195 offset:0
	v_xor_b32_e32 v196, 224, v185
	ds_read_b128 v[76:79], v196 offset:0
	s_waitcnt lgkmcnt(7)
	v_mfma_f32_32x32x16_bf16 v[0:15], v[48:51], v[140:143], 0
	v_mfma_f32_32x32x16_bf16 v[16:31], v[48:51], v[204:207], 0
	s_waitcnt lgkmcnt(6)
	v_mfma_f32_32x32x16_bf16 v[0:15], v[52:55], v[144:147], v[0:15]
	v_mfma_f32_32x32x16_bf16 v[16:31], v[52:55], v[208:211], v[16:31]
	s_waitcnt lgkmcnt(5)
	v_mfma_f32_32x32x16_bf16 v[0:15], v[56:59], v[148:151], v[0:15]
	v_mfma_f32_32x32x16_bf16 v[16:31], v[56:59], v[212:215], v[16:31]
	s_waitcnt lgkmcnt(4)
	v_mfma_f32_32x32x16_bf16 v[0:15], v[60:63], v[152:155], v[0:15]
	v_mfma_f32_32x32x16_bf16 v[16:31], v[60:63], v[216:219], v[16:31]
	s_waitcnt lgkmcnt(3)
	v_mfma_f32_32x32x16_bf16 v[0:15], v[64:67], v[156:159], v[0:15]
	v_mfma_f32_32x32x16_bf16 v[16:31], v[64:67], v[220:223], v[16:31]
	s_waitcnt lgkmcnt(2)
	v_mfma_f32_32x32x16_bf16 v[0:15], v[68:71], v[160:163], v[0:15]
	v_mfma_f32_32x32x16_bf16 v[16:31], v[68:71], v[224:227], v[16:31]
	s_waitcnt lgkmcnt(1)
	v_mfma_f32_32x32x16_bf16 v[0:15], v[72:75], v[164:167], v[0:15]
	v_mfma_f32_32x32x16_bf16 v[16:31], v[72:75], v[228:231], v[16:31]
	s_waitcnt lgkmcnt(0)
	v_mfma_f32_32x32x16_bf16 v[0:15], v[76:79], v[168:171], v[0:15]
	v_mfma_f32_32x32x16_bf16 v[16:31], v[76:79], v[232:235], v[16:31]
	s_and_b32 s0, s27, 3
	s_cmp_eq_u32 s0, 0
	s_cbranch_scc0 .Llru2_id0_0
	v_mfma_f32_32x32x16_bf16 v[32:47], v[48:51], v[172:175], 0
	v_mfma_f32_32x32x16_bf16 v[32:47], v[52:55], v[176:179], v[32:47]

; __device__ __forceinline__ float bf2f(u16 x) { return __uint_as_float(((unsigned)x) << 16); }
; __device__ __forceinline__ float fexp(float x) { return __builtin_amdgcn_exp2f(x * 1.4426950408889634f); }
; __device__ __forceinline__ int crow(int r, int hi) { return (r & 3) + 8 * (r >> 2) + 4 * hi; }
; template <int PASS>
; __device__ __forceinline__ void lru_tile_phase(const Params& p, int jl, int Mrows, char* smem, int tid, int bid) {
;     ...
;         for (int r = 0; r < 16; ++r) {
;           const int tok = tb * 32 + crow(r, hi);
;           const float xc = bf2f(*(const u16*)(xcL + swz256(tok, chl >> 3) + (chl & 7) * 2));
;           const float la = c_sp * __builtin_amdgcn_rcpf(1.f + fexp(-(acc0[r] + c_ba)));
;           const float ii = __builtin_amdgcn_rcpf(1.f + fexp(-(acc1[r] + c_bx)));
;           const float av = fexp(la);
;           aL[(dh * 64 + tok) * 128 + chl] = av;
;           uL[(dh * 64 + tok) * 128 + chl] = __builtin_amdgcn_sqrtf(fmaxf(1.f - av * av, 0.f)) * (ii * xc);
;         }
.Llru2_id1_3:
	s_nop 7
	s_nop 7
	v_fma_f32 v80, v0, v91, v180
	v_fma_f32 v81, v16, v91, v181
	v_exp_f32_e32 v80, v80
	v_exp_f32_e32 v81, v81
	v_add_f32_e32 v80, 1.0, v80
	v_add_f32_e32 v81, 1.0, v81
	v_rcp_f32_e32 v80, v80
	v_rcp_f32_e32 v81, v81
	s_nop 0
	v_mul_f32_e32 v80, v182, v80
	v_mul_f32_e32 v81, v81, v32
	v_exp_f32_e32 v80, v80
	s_nop 0
	v_fma_f32 v82, -v80, v80, 1.0
	v_max_f32_e32 v82, 0, v82
	v_sqrt_f32_e32 v82, v82
	ds_write_b32 v186, v80 offset:16384
	v_mul_f32_e32 v82, v82, v81
	ds_write_b32 v187, v82 offset:16384
	v_fma_f32 v88, v1, v91, v180
	v_fma_f32 v89, v17, v91, v181
	v_exp_f32_e32 v88, v88
	v_exp_f32_e32 v89, v89
	v_add_f32_e32 v88, 1.0, v88
	v_add_f32_e32 v89, 1.0, v89
	v_rcp_f32_e32 v88, v88
	v_rcp_f32_e32 v89, v89
	s_nop 0
	v_mul_f32_e32 v88, v182, v88
	v_mul_f32_e32 v89, v89, v33
	v_exp_f32_e32 v88, v88
	s_nop 0
	v_fma_f32 v90, -v88, v88, 1.0
	v_max_f32_e32 v90, 0, v90
	v_sqrt_f32_e32 v90, v90
	ds_write_b32 v186, v88 offset:16896
	v_mul_f32_e32 v90, v90, v89
	ds_write_b32 v187, v90 offset:16896
	v_fma_f32 v80, v2, v91, v180
	v_fma_f32 v81, v18, v91, v181
	v_exp_f32_e32 v80, v80
	v_exp_f32_e32 v81, v81
	v_add_f32_e32 v80, 1.0, v80
	v_add_f32_e32 v81, 1.0, v81
	v_rcp_f32_e32 v80, v80
	v_rcp_f32_e32 v81, v81
	s_nop 0
	v_mul_f32_e32 v80, v182, v80
	v_mul_f32_e32 v81, v81, v34
	v_exp_f32_e32 v80, v80
	s_nop 0
	v_fma_f32 v82, -v80, v80, 1.0
	v_max_f32_e32 v82, 0, v82
	v_sqrt_f32_e32 v82, v82
	ds_write_b32 v186, v80 offset:17408
	v_mul_f32_e32 v82, v82, v81
	ds_write_b32 v187, v82 offset:17408
	v_fma_f32 v88, v3, v91, v180
	v_fma_f32 v89, v19, v91, v181
	v_exp_f32_e32 v88, v88
	v_exp_f32_e32 v89, v89
	v_add_f32_e32 v88, 1.0, v88
	v_add_f32_e32 v89, 1.0, v89
	v_rcp_f32_e32 v88, v88
	v_rcp_f32_e32 v89, v89
	s_nop 0
	v_mul_f32_e32 v88, v182, v88
	v_mul_f32_e32 v89, v89, v35
	v_exp_f32_e32 v88, v88
	s_nop 0
	v_fma_f32 v90, -v88, v88, 1.0
	v_max_f32_e32 v90, 0, v90
	v_sqrt_f32_e32 v90, v90
	ds_write_b32 v186, v88 offset:17920
	v_mul_f32_e32 v90, v90, v89
	ds_write_b32 v187, v90 offset:17920
	v_fma_f32 v80, v4, v91, v180
	v_fma_f32 v81, v20, v91, v181
	v_exp_f32_e32 v80, v80
	v_exp_f32_e32 v81, v81
	v_add_f32_e32 v80, 1.0, v80
	v_add_f32_e32 v81, 1.0, v81
	v_rcp_f32_e32 v80, v80
	v_rcp_f32_e32 v81, v81
	s_nop 0
	v_mul_f32_e32 v80, v182, v80
	v_mul_f32_e32 v81, v81, v36
	v_exp_f32_e32 v80, v80
	s_nop 0
	v_fma_f32 v82, -v80, v80, 1.0
	v_max_f32_e32 v82, 0, v82
	v_sqrt_f32_e32 v82, v82
	ds_write_b32 v186, v80 offset:20480
	v_mul_f32_e32 v82, v82, v81
	ds_write_b32 v187, v82 offset:20480
	v_fma_f32 v88, v5, v91, v180
	v_fma_f32 v89, v21, v91, v181
	v_exp_f32_e32 v88, v88
	v_exp_f32_e32 v89, v89
	v_add_f32_e32 v88, 1.0, v88
	v_add_f32_e32 v89, 1.0, v89
	v_rcp_f32_e32 v88, v88
	v_rcp_f32_e32 v89, v89
	s_nop 0
	v_mul_f32_e32 v88, v182, v88
	v_mul_f32_e32 v89, v89, v37
	v_exp_f32_e32 v88, v88
	s_nop 0
	v_fma_f32 v90, -v88, v88, 1.0
	v_max_f32_e32 v90, 0, v90
	v_sqrt_f32_e32 v90, v90
	ds_write_b32 v186, v88 offset:20992
	v_mul_f32_e32 v90, v90, v89
	ds_write_b32 v187, v90 offset:20992
	v_fma_f32 v80, v6, v91, v180
	v_fma_f32 v81, v22, v91, v181
	v_exp_f32_e32 v80, v80
	v_exp_f32_e32 v81, v81
	v_add_f32_e32 v80, 1.0, v80
	v_add_f32_e32 v81, 1.0, v81
	v_rcp_f32_e32 v80, v80
	v_rcp_f32_e32 v81, v81
	s_nop 0
	v_mul_f32_e32 v80, v182, v80
	v_mul_f32_e32 v81, v81, v38
	v_exp_f32_e32 v80, v80
	s_nop 0
	v_fma_f32 v82, -v80, v80, 1.0
	v_max_f32_e32 v82, 0, v82
	v_sqrt_f32_e32 v82, v82
	ds_write_b32 v186, v80 offset:21504
	v_mul_f32_e32 v82, v82, v81
	ds_write_b32 v187, v82 offset:21504
	v_fma_f32 v88, v7, v91, v180
	v_fma_f32 v89, v23, v91, v181
	v_exp_f32_e32 v88, v88
	v_exp_f32_e32 v89, v89
	v_add_f32_e32 v88, 1.0, v88
	v_add_f32_e32 v89, 1.0, v89
	v_rcp_f32_e32 v88, v88
	v_rcp_f32_e32 v89, v89
	s_nop 0
	v_mul_f32_e32 v88, v182, v88
	v_mul_f32_e32 v89, v89, v39
	v_exp_f32_e32 v88, v88
	s_nop 0
	v_fma_f32 v90, -v88, v88, 1.0
	v_max_f32_e32 v90, 0, v90
	v_sqrt_f32_e32 v90, v90
	ds_write_b32 v186, v88 offset:22016
	v_mul_f32_e32 v90, v90, v89
	ds_write_b32 v187, v90 offset:22016
	v_fma_f32 v80, v8, v91, v180
	v_fma_f32 v81, v24, v91, v181
	v_exp_f32_e32 v80, v80
	v_exp_f32_e32 v81, v81
	v_add_f32_e32 v80, 1.0, v80
	v_add_f32_e32 v81, 1.0, v81
	v_rcp_f32_e32 v80, v80
	v_rcp_f32_e32 v81, v81
	s_nop 0
	v_mul_f32_e32 v80, v182, v80
	v_mul_f32_e32 v81, v81, v40
	v_exp_f32_e32 v80, v80
	s_nop 0
	v_fma_f32 v82, -v80, v80, 1.0
	v_max_f32_e32 v82, 0, v82
	v_sqrt_f32_e32 v82, v82
	ds_write_b32 v186, v80 offset:24576
	v_mul_f32_e32 v82, v82, v81
	ds_write_b32 v187, v82 offset:24576
	v_fma_f32 v88, v9, v91, v180
	v_fma_f32 v89, v25, v91, v181
	v_exp_f32_e32 v88, v88
	v_exp_f32_e32 v89, v89
	v_add_f32_e32 v88, 1.0, v88
	v_add_f32_e32 v89, 1.0, v89
	v_rcp_f32_e32 v88, v88
	v_rcp_f32_e32 v89, v89
	s_nop 0
	v_mul_f32_e32 v88, v182, v88
	v_mul_f32_e32 v89, v89, v41
	v_exp_f32_e32 v88, v88
	s_nop 0
	v_fma_f32 v90, -v88, v88, 1.0
	v_max_f32_e32 v90, 0, v90
	v_sqrt_f32_e32 v90, v90
	ds_write_b32 v186, v88 offset:25088
; __device__ __forceinline__ float bf2f(u16 x) { return __uint_as_float(((unsigned)x) << 16); }
; __device__ __forceinline__ float fexp(float x) { return __builtin_amdgcn_exp2f(x * 1.4426950408889634f); }
; __device__ __forceinline__ int crow(int r, int hi) { return (r & 3) + 8 * (r >> 2) + 4 * hi; }
; template <int PASS>
; __device__ __forceinline__ void lru_tile_phase(const Params& p, int jl, int Mrows, char* smem, int tid, int bid) {
;     ...
;       const u16* xsrc = P2 + (size_t)(rowbase - sloc) * 2048 + 1024 + col;
; #pragma unroll
;       for (int i = 0; i < 19; ++i) {
;         const int s = sloc + t0 + i - 2;
;         const int sc = s < 0 ? 0 : (s >= TT ? TT - 1 : s);
;         xraw[i] = xsrc[(size_t)sc * 2048];
;       }
;     ...
;         for (int r = 0; r < 16; ++r) {
;           const int tok = tb * 32 + crow(r, hi);
;           const float xc = bf2f(*(const u16*)(xcL + swz256(tok, chl >> 3) + (chl & 7) * 2));
;           const float la = c_sp * __builtin_amdgcn_rcpf(1.f + fexp(-(acc0[r] + c_ba)));
;           const float ii = __builtin_amdgcn_rcpf(1.f + fexp(-(acc1[r] + c_bx)));
;           const float av = fexp(la);
;           aL[(dh * 64 + tok) * 128 + chl] = av;
;           uL[(dh * 64 + tok) * 128 + chl] = __builtin_amdgcn_sqrtf(fmaxf(1.f - av * av, 0.f)) * (ii * xc);
;         }
;       }
;     }
;     __syncthreads();
;     if (tid < 256) {
	v_mul_f32_e32 v90, v90, v89
	ds_write_b32 v187, v90 offset:25088
	v_fma_f32 v80, v10, v91, v180
	v_fma_f32 v81, v26, v91, v181
	v_exp_f32_e32 v80, v80
	v_exp_f32_e32 v81, v81
	v_add_f32_e32 v80, 1.0, v80
	v_add_f32_e32 v81, 1.0, v81
	v_rcp_f32_e32 v80, v80
	v_rcp_f32_e32 v81, v81
	s_nop 0
	v_mul_f32_e32 v80, v182, v80
	v_mul_f32_e32 v81, v81, v42
	v_exp_f32_e32 v80, v80
	s_nop 0
	v_fma_f32 v82, -v80, v80, 1.0
	v_max_f32_e32 v82, 0, v82
	v_sqrt_f32_e32 v82, v82
	ds_write_b32 v186, v80 offset:25600
	v_mul_f32_e32 v82, v82, v81
	ds_write_b32 v187, v82 offset:25600
	v_fma_f32 v88, v11, v91, v180
	v_fma_f32 v89, v27, v91, v181
	v_exp_f32_e32 v88, v88
	v_exp_f32_e32 v89, v89
	v_add_f32_e32 v88, 1.0, v88
	v_add_f32_e32 v89, 1.0, v89
	v_rcp_f32_e32 v88, v88
	v_rcp_f32_e32 v89, v89
	s_nop 0
	v_mul_f32_e32 v88, v182, v88
	v_mul_f32_e32 v89, v89, v43
	v_exp_f32_e32 v88, v88
	s_nop 0
	v_fma_f32 v90, -v88, v88, 1.0
	v_max_f32_e32 v90, 0, v90
	v_sqrt_f32_e32 v90, v90
	ds_write_b32 v186, v88 offset:26112
	v_mul_f32_e32 v90, v90, v89
	ds_write_b32 v187, v90 offset:26112
	v_fma_f32 v80, v12, v91, v180
	v_fma_f32 v81, v28, v91, v181
	v_exp_f32_e32 v80, v80
	v_exp_f32_e32 v81, v81
	v_add_f32_e32 v80, 1.0, v80
	v_add_f32_e32 v81, 1.0, v81
	v_rcp_f32_e32 v80, v80
	v_rcp_f32_e32 v81, v81
	s_nop 0
	v_mul_f32_e32 v80, v182, v80
	v_mul_f32_e32 v81, v81, v44
	v_exp_f32_e32 v80, v80
	s_nop 0
	v_fma_f32 v82, -v80, v80, 1.0
	v_max_f32_e32 v82, 0, v82
	v_sqrt_f32_e32 v82, v82
	ds_write_b32 v186, v80 offset:28672
	v_mul_f32_e32 v82, v82, v81
	ds_write_b32 v187, v82 offset:28672
	v_fma_f32 v88, v13, v91, v180
	v_fma_f32 v89, v29, v91, v181
	v_exp_f32_e32 v88, v88
	v_exp_f32_e32 v89, v89
	v_add_f32_e32 v88, 1.0, v88
	v_add_f32_e32 v89, 1.0, v89
	v_rcp_f32_e32 v88, v88
	v_rcp_f32_e32 v89, v89
	s_nop 0
	v_mul_f32_e32 v88, v182, v88
	v_mul_f32_e32 v89, v89, v45
	v_exp_f32_e32 v88, v88
	s_nop 0
	v_fma_f32 v90, -v88, v88, 1.0
	v_max_f32_e32 v90, 0, v90
	v_sqrt_f32_e32 v90, v90
	ds_write_b32 v186, v88 offset:29184
	v_mul_f32_e32 v90, v90, v89
	ds_write_b32 v187, v90 offset:29184
	v_fma_f32 v80, v14, v91, v180
	v_fma_f32 v81, v30, v91, v181
	v_exp_f32_e32 v80, v80
	v_exp_f32_e32 v81, v81
	v_add_f32_e32 v80, 1.0, v80
	v_add_f32_e32 v81, 1.0, v81
	v_rcp_f32_e32 v80, v80
	v_rcp_f32_e32 v81, v81
	s_nop 0
	v_mul_f32_e32 v80, v182, v80
	v_mul_f32_e32 v81, v81, v46
	v_exp_f32_e32 v80, v80
	s_nop 0
	v_fma_f32 v82, -v80, v80, 1.0
	v_max_f32_e32 v82, 0, v82
	v_sqrt_f32_e32 v82, v82
	ds_write_b32 v186, v80 offset:29696
	v_mul_f32_e32 v82, v82, v81
	ds_write_b32 v187, v82 offset:29696
	v_fma_f32 v88, v15, v91, v180
	v_fma_f32 v89, v31, v91, v181
	v_exp_f32_e32 v88, v88
	v_exp_f32_e32 v89, v89
	v_add_f32_e32 v88, 1.0, v88
	v_add_f32_e32 v89, 1.0, v89
	v_rcp_f32_e32 v88, v88
	v_rcp_f32_e32 v89, v89
	s_nop 0
	v_mul_f32_e32 v88, v182, v88
	v_mul_f32_e32 v89, v89, v47
	v_exp_f32_e32 v88, v88
	s_nop 0
	v_fma_f32 v90, -v88, v88, 1.0
	v_max_f32_e32 v90, 0, v90
	v_sqrt_f32_e32 v90, v90
	ds_write_b32 v186, v88 offset:30208
	v_mul_f32_e32 v90, v90, v89
	ds_write_b32 v187, v90 offset:30208
	s_waitcnt lgkmcnt(0)
	s_barrier
	s_add_u32 s0, s6, s71
	s_cmp_lt_u32 s0, 0x1100
	s_cbranch_scc0 .Llru2_nopf
	s_lshr_b32 s10, s0, 3
	s_and_b32 s11, s0, 7
	s_movk_i32 s0, 0x1000
	s_cmp_lt_u32 s10, 512
	s_cselect_b32 s4, 0, 512
	s_cselect_b32 s5, 0, 0x8000
	s_cselect_b32 s1, 63, 3
	s_cselect_b32 s21, s0, 0x100
	s_sub_u32 s0, s10, s4
	s_lshl_b32 s20, s0, 6
	s_add_u32 s20, s20, s5
	s_and_b32 s10, s0, s1
	s_lshl_b32 s10, s10, 6
	s_cmp_eq_u32 s10, 0
	s_cselect_b32 s4, 0, -2
	s_add_u32 s0, s10, 64
	s_cmp_eq_u32 s0, s21
	s_cselect_b32 s5, 63, 0x41
	s_lshl_b32 s0, s20, 12
	s_lshl_b32 s1, s11, 8
	s_add_u32 s0, s0, s1
	s_add_u32 s0, s92, s0
	s_addc_u32 s1, s93, 0
	s_sub_u32 s0, s0, 0x1800
	s_subb_u32 s1, s1, 0
	v_add_u32_e32 v44, -2, v190
	v_max_i32_e32 v49, s4, v44
	v_min_i32_e32 v49, s5, v49
	v_add_u32_e32 v195, 2, v49
	v_lshl_add_u32 v195, v195, 12, v191
	global_load_dwordx4 v[56:59], v195, s[0:1]
	v_add_u32_e32 v45, -1, v190
	v_max_i32_e32 v50, s4, v45
	v_min_i32_e32 v50, s5, v50
	v_add_u32_e32 v195, 2, v50
	v_lshl_add_u32 v195, v195, 12, v191
	global_load_dwordx4 v[60:63], v195, s[0:1]
	v_add_u32_e32 v46, 0, v190
	v_max_i32_e32 v51, s4, v46
	v_min_i32_e32 v51, s5, v51
	v_add_u32_e32 v195, 2, v51
	v_lshl_add_u32 v195, v195, 12, v191
	global_load_dwordx4 v[64:67], v195, s[0:1]
	v_add_u32_e32 v47, 1, v190
	v_max_i32_e32 v52, s4, v47
	v_min_i32_e32 v52, s5, v52
	v_add_u32_e32 v195, 2, v52
	v_lshl_add_u32 v195, v195, 12, v191
	global_load_dwordx4 v[68:71], v195, s[0:1]
	v_add_u32_e32 v48, 2, v190
	v_max_i32_e32 v53, s4, v48
	v_min_i32_e32 v53, s5, v53
	v_add_u32_e32 v195, 2, v53
	v_lshl_add_u32 v195, v195, 12, v191
	global_load_dwordx4 v[72:75], v195, s[0:1]
	s_mov_b32 s10, 1
	s_branch .Llru2_pfdone
.Llru2_nopf:
	s_mov_b32 s10, 0
.Llru2_pfdone:
	s_cmp_gt_u32 s27, 3
	s_cbranch_scc1 .Llru2_scan_done
	s_cmp_eq_u32 s10, 0
	s_cbranch_scc1 .Llru2_cw0
	s_waitcnt vmcnt(5)
	s_branch .Llru2_cwd

; template <int PASS>
; __device__ __forceinline__ void lru_tile_phase(const Params& p, int jl, int Mrows, char* smem, int tid, int bid) {
;     ...
;     if (tid < 256) {
;       const int dir = tid >> 7, ch = tid & 127;
;       const size_t sidx = (size_t)(tt * 2 + dir) * 1024 + n * 128 + ch;
;       float hst = 0.f, ap = 1.f;
;       if (PASS == 2) hst = carry_in;
;       const float* ap_ = aL + (dir * 64) * 128 + ch;
;       float* up_ = uL + (dir * 64) * 128 + ch;
; #pragma unroll 1
;       for (int i0 = 0; i0 < 64; i0 += 16) {
;         float av[16], uv[16];
; #pragma unroll
;         for (int k = 0; k < 16; ++k) { const int t = dir ? 63 - (i0 + k) : i0 + k; av[k] = ap_[t * 128]; uv[k] = up_[t * 128]; }
; #pragma unroll
;         for (int k = 0; k < 16; ++k) { hst = fmaf(av[k], hst, uv[k]); if (PASS == 1) ap *= av[k]; else uv[k] = hst; }
;         if (PASS == 2) {
; #pragma unroll
;           for (int k = 0; k < 16; ++k) { const int t = dir ? 63 - (i0 + k) : i0 + k; up_[t * 128] = uv[k]; }
;         }
;       }
.Llru2_cwd:
	v_mov_b32_e32 v96, v252
	v_add_u32_e32 v195, 0x10000, v188
	s_cmp_gt_u32 s27, 1
	s_cbranch_scc1 .Llru2_scan_bwd
	ds_read2st64_b32 v[0:1], v188 offset0:0 offset1:2
	ds_read2st64_b32 v[2:3], v188 offset0:4 offset1:6
	ds_read2st64_b32 v[4:5], v188 offset0:8 offset1:10
	ds_read2st64_b32 v[6:7], v188 offset0:12 offset1:14
	ds_read2st64_b32 v[8:9], v195 offset0:0 offset1:2
	ds_read2st64_b32 v[10:11], v195 offset0:4 offset1:6
	ds_read2st64_b32 v[12:13], v195 offset0:8 offset1:10
	ds_read2st64_b32 v[14:15], v195 offset0:12 offset1:14
	s_waitcnt lgkmcnt(0)
	ds_read2st64_b32 v[16:17], v188 offset0:16 offset1:18
	ds_read2st64_b32 v[18:19], v188 offset0:20 offset1:22
	ds_read2st64_b32 v[20:21], v188 offset0:24 offset1:26
	ds_read2st64_b32 v[22:23], v188 offset0:28 offset1:30
	ds_read2st64_b32 v[24:25], v195 offset0:16 offset1:18
	ds_read2st64_b32 v[26:27], v195 offset0:20 offset1:22
	ds_read2st64_b32 v[28:29], v195 offset0:24 offset1:26
	ds_read2st64_b32 v[30:31], v195 offset0:28 offset1:30
	v_fma_f32 v96, v0, v96, v8
	v_mov_b32_e32 v32, v96
	v_fma_f32 v96, v1, v96, v9
	v_mov_b32_e32 v33, v96
	v_fma_f32 v96, v2, v96, v10
	v_mov_b32_e32 v34, v96
	v_fma_f32 v96, v3, v96, v11
	v_mov_b32_e32 v35, v96
	v_fma_f32 v96, v4, v96, v12
	v_mov_b32_e32 v36, v96
	v_fma_f32 v96, v5, v96, v13
	v_mov_b32_e32 v37, v96
	v_fma_f32 v96, v6, v96, v14
	v_mov_b32_e32 v38, v96
	v_fma_f32 v96, v7, v96, v15
	v_mov_b32_e32 v39, v96
	ds_write2st64_b32 v195, v32, v33 offset0:0 offset1:2
	ds_write2st64_b32 v195, v34, v35 offset0:4 offset1:6
	ds_write2st64_b32 v195, v36, v37 offset0:8 offset1:10
	ds_write2st64_b32 v195, v38, v39 offset0:12 offset1:14
	s_waitcnt lgkmcnt(0)
	ds_read2st64_b32 v[0:1], v188 offset0:32 offset1:34
	ds_read2st64_b32 v[2:3], v188 offset0:36 offset1:38
	ds_read2st64_b32 v[4:5], v188 offset0:40 offset1:42
	ds_read2st64_b32 v[6:7], v188 offset0:44 offset1:46
	ds_read2st64_b32 v[8:9], v195 offset0:32 offset1:34
	ds_read2st64_b32 v[10:11], v195 offset0:36 offset1:38
	ds_read2st64_b32 v[12:13], v195 offset0:40 offset1:42
	ds_read2st64_b32 v[14:15], v195 offset0:44 offset1:46
	v_fma_f32 v96, v16, v96, v24
	v_mov_b32_e32 v32, v96
	v_fma_f32 v96, v17, v96, v25
	v_mov_b32_e32 v33, v96
	v_fma_f32 v96, v18, v96, v26
	v_mov_b32_e32 v34, v96
	v_fma_f32 v96, v19, v96, v27
	v_mov_b32_e32 v35, v96
	v_fma_f32 v96, v20, v96, v28
	v_mov_b32_e32 v36, v96
	v_fma_f32 v96, v21, v96, v29
	v_mov_b32_e32 v37, v96
	v_fma_f32 v96, v22, v96, v30
	v_mov_b32_e32 v38, v96
	v_fma_f32 v96, v23, v96, v31
	v_mov_b32_e32 v39, v96
	ds_write2st64_b32 v195, v32, v33 offset0:16 offset1:18
	ds_write2st64_b32 v195, v34, v35 offset0:20 offset1:22
	ds_write2st64_b32 v195, v36, v37 offset0:24 offset1:26
	ds_write2st64_b32 v195, v38, v39 offset0:28 offset1:30
	s_waitcnt lgkmcnt(0)
	ds_read2st64_b32 v[16:17], v188 offset0:48 offset1:50
	ds_read2st64_b32 v[18:19], v188 offset0:52 offset1:54
	ds_read2st64_b32 v[20:21], v188 offset0:56 offset1:58
	ds_read2st64_b32 v[22:23], v188 offset0:60 offset1:62
	ds_read2st64_b32 v[24:25], v195 offset0:48 offset1:50
	ds_read2st64_b32 v[26:27], v195 offset0:52 offset1:54
	ds_read2st64_b32 v[28:29], v195 offset0:56 offset1:58
	ds_read2st64_b32 v[30:31], v195 offset0:60 offset1:62
	v_fma_f32 v96, v0, v96, v8
	v_mov_b32_e32 v32, v96
	v_fma_f32 v96, v1, v96, v9
	v_mov_b32_e32 v33, v96
	v_fma_f32 v96, v2, v96, v10
	v_mov_b32_e32 v34, v96
	v_fma_f32 v96, v3, v96, v11
	v_mov_b32_e32 v35, v96
	v_fma_f32 v96, v4, v96, v12
	v_mov_b32_e32 v36, v96
	v_fma_f32 v96, v5, v96, v13
	v_mov_b32_e32 v37, v96
	v_fma_f32 v96, v6, v96, v14
	v_mov_b32_e32 v38, v96
	v_fma_f32 v96, v7, v96, v15
	v_mov_b32_e32 v39, v96
	ds_write2st64_b32 v195, v32, v33 offset0:32 offset1:34
	ds_write2st64_b32 v195, v34, v35 offset0:36 offset1:38
	ds_write2st64_b32 v195, v36, v37 offset0:40 offset1:42
	ds_write2st64_b32 v195, v38, v39 offset0:44 offset1:46
	s_waitcnt lgkmcnt(0)
	ds_read2st64_b32 v[0:1], v188 offset0:64 offset1:66
	ds_read2st64_b32 v[2:3], v188 offset0:68 offset1:70
	ds_read2st64_b32 v[4:5], v188 offset0:72 offset1:74
	ds_read2st64_b32 v[6:7], v188 offset0:76 offset1:78
	ds_read2st64_b32 v[8:9], v195 offset0:64 offset1:66
	ds_read2st64_b32 v[10:11], v195 offset0:68 offset1:70
	ds_read2st64_b32 v[12:13], v195 offset0:72 offset1:74
	ds_read2st64_b32 v[14:15], v195 offset0:76 offset1:78
	v_fma_f32 v96, v16, v96, v24
	v_mov_b32_e32 v32, v96
	v_fma_f32 v96, v17, v96, v25
	v_mov_b32_e32 v33, v96
	v_fma_f32 v96, v18, v96, v26
	v_mov_b32_e32 v34, v96
	v_fma_f32 v96, v19, v96, v27
	v_mov_b32_e32 v35, v96
	v_fma_f32 v96, v20, v96, v28
	v_mov_b32_e32 v36, v96
	v_fma_f32 v96, v21, v96, v29
	v_mov_b32_e32 v37, v96
	v_fma_f32 v96, v22, v96, v30
	v_mov_b32_e32 v38, v96
	v_fma_f32 v96, v23, v96, v31
	v_mov_b32_e32 v39, v96
	ds_write2st64_b32 v195, v32, v33 offset0:48 offset1:50
	ds_write2st64_b32 v195, v34, v35 offset0:52 offset1:54
	ds_write2st64_b32 v195, v36, v37 offset0:56 offset1:58
	ds_write2st64_b32 v195, v38, v39 offset0:60 offset1:62
	s_waitcnt lgkmcnt(0)
; template <int PASS>
; __device__ __forceinline__ void lru_tile_phase(const Params& p, int jl, int Mrows, char* smem, int tid, int bid) {
;     ...
; #pragma unroll 1
;       for (int i0 = 0; i0 < 64; i0 += 16) {
;         float av[16], uv[16];
; #pragma unroll
;         for (int k = 0; k < 16; ++k) { const int t = dir ? 63 - (i0 + k) : i0 + k; av[k] = ap_[t * 128]; uv[k] = up_[t * 128]; }
; #pragma unroll
;         for (int k = 0; k < 16; ++k) { hst = fmaf(av[k], hst, uv[k]); if (PASS == 1) ap *= av[k]; else uv[k] = hst; }
;         if (PASS == 2) {
; #pragma unroll
;           for (int k = 0; k < 16; ++k) { const int t = dir ? 63 - (i0 + k) : i0 + k; up_[t * 128] = uv[k]; }
;         }
;       }
	ds_read2st64_b32 v[16:17], v188 offset0:80 offset1:82
	ds_read2st64_b32 v[18:19], v188 offset0:84 offset1:86
	ds_read2st64_b32 v[20:21], v188 offset0:88 offset1:90
	ds_read2st64_b32 v[22:23], v188 offset0:92 offset1:94
	ds_read2st64_b32 v[24:25], v195 offset0:80 offset1:82
	ds_read2st64_b32 v[26:27], v195 offset0:84 offset1:86
	ds_read2st64_b32 v[28:29], v195 offset0:88 offset1:90
	ds_read2st64_b32 v[30:31], v195 offset0:92 offset1:94
	v_fma_f32 v96, v0, v96, v8
	v_mov_b32_e32 v32, v96
	v_fma_f32 v96, v1, v96, v9
	v_mov_b32_e32 v33, v96
	v_fma_f32 v96, v2, v96, v10
	v_mov_b32_e32 v34, v96
	v_fma_f32 v96, v3, v96, v11
	v_mov_b32_e32 v35, v96
	v_fma_f32 v96, v4, v96, v12
	v_mov_b32_e32 v36, v96
	v_fma_f32 v96, v5, v96, v13
	v_mov_b32_e32 v37, v96
	v_fma_f32 v96, v6, v96, v14
	v_mov_b32_e32 v38, v96
	v_fma_f32 v96, v7, v96, v15
	v_mov_b32_e32 v39, v96
	ds_write2st64_b32 v195, v32, v33 offset0:64 offset1:66
	ds_write2st64_b32 v195, v34, v35 offset0:68 offset1:70
	ds_write2st64_b32 v195, v36, v37 offset0:72 offset1:74
	ds_write2st64_b32 v195, v38, v39 offset0:76 offset1:78
	s_waitcnt lgkmcnt(0)
	ds_read2st64_b32 v[0:1], v188 offset0:96 offset1:98
	ds_read2st64_b32 v[2:3], v188 offset0:100 offset1:102
	ds_read2st64_b32 v[4:5], v188 offset0:104 offset1:106
	ds_read2st64_b32 v[6:7], v188 offset0:108 offset1:110
	ds_read2st64_b32 v[8:9], v195 offset0:96 offset1:98
	ds_read2st64_b32 v[10:11], v195 offset0:100 offset1:102
	ds_read2st64_b32 v[12:13], v195 offset0:104 offset1:106
	ds_read2st64_b32 v[14:15], v195 offset0:108 offset1:110
	v_fma_f32 v96, v16, v96, v24
	v_mov_b32_e32 v32, v96
	v_fma_f32 v96, v17, v96, v25
	v_mov_b32_e32 v33, v96
	v_fma_f32 v96, v18, v96, v26
	v_mov_b32_e32 v34, v96
	v_fma_f32 v96, v19, v96, v27
	v_mov_b32_e32 v35, v96
	v_fma_f32 v96, v20, v96, v28
	v_mov_b32_e32 v36, v96
	v_fma_f32 v96, v21, v96, v29
	v_mov_b32_e32 v37, v96
	v_fma_f32 v96, v22, v96, v30
	v_mov_b32_e32 v38, v96
	v_fma_f32 v96, v23, v96, v31
	v_mov_b32_e32 v39, v96
	ds_write2st64_b32 v195, v32, v33 offset0:80 offset1:82
	ds_write2st64_b32 v195, v34, v35 offset0:84 offset1:86
	ds_write2st64_b32 v195, v36, v37 offset0:88 offset1:90
	ds_write2st64_b32 v195, v38, v39 offset0:92 offset1:94
	s_waitcnt lgkmcnt(0)
	ds_read2st64_b32 v[16:17], v188 offset0:112 offset1:114
	ds_read2st64_b32 v[18:19], v188 offset0:116 offset1:118
	ds_read2st64_b32 v[20:21], v188 offset0:120 offset1:122
	ds_read2st64_b32 v[22:23], v188 offset0:124 offset1:126
	ds_read2st64_b32 v[24:25], v195 offset0:112 offset1:114
	ds_read2st64_b32 v[26:27], v195 offset0:116 offset1:118
	ds_read2st64_b32 v[28:29], v195 offset0:120 offset1:122
	ds_read2st64_b32 v[30:31], v195 offset0:124 offset1:126
	v_fma_f32 v96, v0, v96, v8
	v_mov_b32_e32 v32, v96
	v_fma_f32 v96, v1, v96, v9
	v_mov_b32_e32 v33, v96
	v_fma_f32 v96, v2, v96, v10
	v_mov_b32_e32 v34, v96
	v_fma_f32 v96, v3, v96, v11
	v_mov_b32_e32 v35, v96
	v_fma_f32 v96, v4, v96, v12
	v_mov_b32_e32 v36, v96
	v_fma_f32 v96, v5, v96, v13
	v_mov_b32_e32 v37, v96
	v_fma_f32 v96, v6, v96, v14
	v_mov_b32_e32 v38, v96
	v_fma_f32 v96, v7, v96, v15
	v_mov_b32_e32 v39, v96
	ds_write2st64_b32 v195, v32, v33 offset0:96 offset1:98
	ds_write2st64_b32 v195, v34, v35 offset0:100 offset1:102
	ds_write2st64_b32 v195, v36, v37 offset0:104 offset1:106
	ds_write2st64_b32 v195, v38, v39 offset0:108 offset1:110
	s_waitcnt lgkmcnt(0)
	v_fma_f32 v96, v16, v96, v24
	v_mov_b32_e32 v32, v96
	v_fma_f32 v96, v17, v96, v25
	v_mov_b32_e32 v33, v96
	v_fma_f32 v96, v18, v96, v26
	v_mov_b32_e32 v34, v96
	v_fma_f32 v96, v19, v96, v27
	v_mov_b32_e32 v35, v96
	v_fma_f32 v96, v20, v96, v28
	v_mov_b32_e32 v36, v96
	v_fma_f32 v96, v21, v96, v29
	v_mov_b32_e32 v37, v96
	v_fma_f32 v96, v22, v96, v30
	v_mov_b32_e32 v38, v96
	v_fma_f32 v96, v23, v96, v31
	v_mov_b32_e32 v39, v96
	ds_write2st64_b32 v195, v32, v33 offset0:112 offset1:114
	ds_write2st64_b32 v195, v34, v35 offset0:116 offset1:118
	ds_write2st64_b32 v195, v36, v37 offset0:120 offset1:122
	ds_write2st64_b32 v195, v38, v39 offset0:124 offset1:126
	s_branch .Llru2_scan_store

; template <int PASS>
; __device__ __forceinline__ void lru_tile_phase(const Params& p, int jl, int Mrows, char* smem, int tid, int bid) {
;     ...
;         for (int k = 0; k < 16; ++k) { hst = fmaf(av[k], hst, uv[k]); if (PASS == 1) ap *= av[k]; else uv[k] = hst; }
;         if (PASS == 2) {
; #pragma unroll
;           for (int k = 0; k < 16; ++k) { const int t = dir ? 63 - (i0 + k) : i0 + k; up_[t * 128] = uv[k]; }
;         }
;       }
;       if (PASS == 1) summ[sidx] = make_float2(ap, hst);
;     }
;     if (PASS == 2) {
;       __syncthreads();
.Llru2_scan_store:
.Llru2_scan_done:
	s_cmp_eq_u32 s10, 0
	s_cbranch_scc1 .Llru2_gw0
	s_waitcnt vmcnt(5) lgkmcnt(0)
	s_branch .Llru2_gwd

; __device__ __forceinline__ u16 f2bf(float x) { return (u16)(cvtpk(x, 0.f) & 0xffffu); }
; __device__ __forceinline__ float fexp(float x) { return __builtin_amdgcn_exp2f(x * 1.4426950408889634f); }
; template <int PASS>
; __device__ __forceinline__ void lru_tile_phase(const Params& p, int jl, int Mrows, char* smem, int tid, int bid) {
;     ...
;     if (PASS == 2) {
;       __syncthreads();
;       const int ch = tid & 127, tg = tid >> 7;
;       const int col = n * 128 + ch;
;       float hsv[16];
; #pragma unroll
;       for (int i = 0; i < 16; ++i) { const int t = tg * 16 + i; hsv[i] = uL[(0 * 64 + t) * 128 + ch] + uL[(1 * 64 + t) * 128 + ch]; }
; #pragma unroll
;       for (int i = 0; i < 16; ++i) {
;         const int t = tg * 16 + i;
;         const float hs = hsv[i];
;         const float gt = __uint_as_float(gv[i] << 16);
;         const float z2 = 1.5957691216057308f * (gt + 0.044715f * gt * gt * gt);
;         const float gl = gt * __builtin_amdgcn_rcpf(1.f + fexp(-z2));
;         H[(size_t)(rowbase + t) * 1024 + col] = f2bf(hs * gl);
;       }
;     }
;     __syncthreads();
.Llru2_gwd:
	s_barrier
	ds_read_b128 v[0:3], v189 offset:0
	ds_read_b128 v[4:7], v189 offset:16
	ds_read_b128 v[8:11], v189 offset:32
	ds_read_b128 v[12:15], v189 offset:48
	ds_read_b128 v[16:19], v189 offset:32768
	ds_read_b128 v[20:23], v189 offset:32784
	ds_read_b128 v[24:27], v189 offset:32800
	ds_read_b128 v[28:31], v189 offset:32816
	s_lshl_b32 s0, s9, 11
	s_lshl_b32 s1, s7, 8
	s_add_u32 s0, s0, s1
	s_add_u32 s0, s28, s0
	s_addc_u32 s1, s29, 0
	s_waitcnt lgkmcnt(0)
	v_add_f32_e32 v0, v0, v16
	v_lshlrev_b32_e32 v80, 16, v92
	v_mul_f32_e32 v81, 0x3d372713, v80
	v_mul_f32_e32 v81, v81, v80
	v_fma_f32 v81, v81, v80, v80
	v_mul_f32_e32 v81, 0x3fcc422a, v81
	v_mul_f32_e32 v81, 0xbfb8aa3b, v81
	v_exp_f32_e32 v81, v81
	s_nop 0
	v_add_f32_e32 v81, 1.0, v81
	v_rcp_f32_e32 v81, v81
	s_nop 0
	v_mul_f32_e32 v81, v80, v81
	v_mul_f32_e32 v0, v0, v81
	v_add_f32_e32 v1, v1, v17
	v_and_b32_e32 v80, 0xffff0000, v92
	v_mul_f32_e32 v81, 0x3d372713, v80
	v_mul_f32_e32 v81, v81, v80
	v_fma_f32 v81, v81, v80, v80
	v_mul_f32_e32 v81, 0x3fcc422a, v81
	v_mul_f32_e32 v81, 0xbfb8aa3b, v81
	v_exp_f32_e32 v81, v81
	s_nop 0
	v_add_f32_e32 v81, 1.0, v81
	v_rcp_f32_e32 v81, v81
	s_nop 0
	v_mul_f32_e32 v81, v80, v81
	v_mul_f32_e32 v1, v1, v81
	v_add_f32_e32 v2, v2, v18
	v_lshlrev_b32_e32 v80, 16, v93
	v_mul_f32_e32 v81, 0x3d372713, v80
	v_mul_f32_e32 v81, v81, v80
	v_fma_f32 v81, v81, v80, v80
	v_mul_f32_e32 v81, 0x3fcc422a, v81
	v_mul_f32_e32 v81, 0xbfb8aa3b, v81
	v_exp_f32_e32 v81, v81
	s_nop 0
	v_add_f32_e32 v81, 1.0, v81
	v_rcp_f32_e32 v81, v81
	s_nop 0
	v_mul_f32_e32 v81, v80, v81
	v_mul_f32_e32 v2, v2, v81
	v_add_f32_e32 v3, v3, v19
	v_and_b32_e32 v80, 0xffff0000, v93
	v_mul_f32_e32 v81, 0x3d372713, v80
	v_mul_f32_e32 v81, v81, v80
	v_fma_f32 v81, v81, v80, v80
	v_mul_f32_e32 v81, 0x3fcc422a, v81
	v_mul_f32_e32 v81, 0xbfb8aa3b, v81
	v_exp_f32_e32 v81, v81
	s_nop 0
	v_add_f32_e32 v81, 1.0, v81
	v_rcp_f32_e32 v81, v81
	s_nop 0
	v_mul_f32_e32 v81, v80, v81
	v_mul_f32_e32 v3, v3, v81
	v_add_f32_e32 v4, v4, v20
	v_lshlrev_b32_e32 v80, 16, v94
	v_mul_f32_e32 v81, 0x3d372713, v80
	v_mul_f32_e32 v81, v81, v80
	v_fma_f32 v81, v81, v80, v80
	v_mul_f32_e32 v81, 0x3fcc422a, v81
	v_mul_f32_e32 v81, 0xbfb8aa3b, v81
	v_exp_f32_e32 v81, v81
	s_nop 0
	v_add_f32_e32 v81, 1.0, v81
	v_rcp_f32_e32 v81, v81
	s_nop 0
	v_mul_f32_e32 v81, v80, v81
	v_mul_f32_e32 v4, v4, v81
	v_add_f32_e32 v5, v5, v21
	v_and_b32_e32 v80, 0xffff0000, v94
	v_mul_f32_e32 v81, 0x3d372713, v80
	v_mul_f32_e32 v81, v81, v80
	v_fma_f32 v81, v81, v80, v80
	v_mul_f32_e32 v81, 0x3fcc422a, v81
	v_mul_f32_e32 v81, 0xbfb8aa3b, v81
	v_exp_f32_e32 v81, v81
	s_nop 0
	v_add_f32_e32 v81, 1.0, v81
	v_rcp_f32_e32 v81, v81
	s_nop 0
	v_mul_f32_e32 v81, v80, v81
	v_mul_f32_e32 v5, v5, v81
	v_add_f32_e32 v6, v6, v22
	v_lshlrev_b32_e32 v80, 16, v95
	v_mul_f32_e32 v81, 0x3d372713, v80
	v_mul_f32_e32 v81, v81, v80
	v_fma_f32 v81, v81, v80, v80
	v_mul_f32_e32 v81, 0x3fcc422a, v81
	v_mul_f32_e32 v81, 0xbfb8aa3b, v81
	v_exp_f32_e32 v81, v81
	s_nop 0
	v_add_f32_e32 v81, 1.0, v81
	v_rcp_f32_e32 v81, v81
	s_nop 0
	v_mul_f32_e32 v81, v80, v81
	v_mul_f32_e32 v6, v6, v81
	v_add_f32_e32 v7, v7, v23
	v_and_b32_e32 v80, 0xffff0000, v95
	v_mul_f32_e32 v81, 0x3d372713, v80
	v_mul_f32_e32 v81, v81, v80
	v_fma_f32 v81, v81, v80, v80
	v_mul_f32_e32 v81, 0x3fcc422a, v81
	v_mul_f32_e32 v81, 0xbfb8aa3b, v81
	v_exp_f32_e32 v81, v81
	s_nop 0
	v_add_f32_e32 v81, 1.0, v81
	v_rcp_f32_e32 v81, v81
	s_nop 0
	v_mul_f32_e32 v81, v80, v81
	v_mul_f32_e32 v7, v7, v81
	v_add_f32_e32 v8, v8, v24
	v_lshlrev_b32_e32 v80, 16, v244
	v_mul_f32_e32 v81, 0x3d372713, v80
	v_mul_f32_e32 v81, v81, v80
	v_fma_f32 v81, v81, v80, v80
	v_mul_f32_e32 v81, 0x3fcc422a, v81
	v_mul_f32_e32 v81, 0xbfb8aa3b, v81
	v_exp_f32_e32 v81, v81
	s_nop 0
	v_add_f32_e32 v81, 1.0, v81
	v_rcp_f32_e32 v81, v81
	s_nop 0
	v_mul_f32_e32 v81, v80, v81
	v_mul_f32_e32 v8, v8, v81
	v_add_f32_e32 v9, v9, v25
	v_and_b32_e32 v80, 0xffff0000, v244
	v_mul_f32_e32 v81, 0x3d372713, v80
	v_mul_f32_e32 v81, v81, v80
	v_fma_f32 v81, v81, v80, v80
	v_mul_f32_e32 v81, 0x3fcc422a, v81
	v_mul_f32_e32 v81, 0xbfb8aa3b, v81
	v_exp_f32_e32 v81, v81
	s_nop 0
	v_add_f32_e32 v81, 1.0, v81
	v_rcp_f32_e32 v81, v81
	s_nop 0
	v_mul_f32_e32 v81, v80, v81
	v_mul_f32_e32 v9, v9, v81
	v_add_f32_e32 v10, v10, v26
	v_lshlrev_b32_e32 v80, 16, v245
	v_mul_f32_e32 v81, 0x3d372713, v80
	v_mul_f32_e32 v81, v81, v80
	v_fma_f32 v81, v81, v80, v80
	v_mul_f32_e32 v81, 0x3fcc422a, v81
	v_mul_f32_e32 v81, 0xbfb8aa3b, v81
	v_exp_f32_e32 v81, v81
	s_nop 0
	v_add_f32_e32 v81, 1.0, v81
	v_rcp_f32_e32 v81, v81
	s_nop 0
	v_mul_f32_e32 v81, v80, v81
	v_mul_f32_e32 v10, v10, v81
	v_add_f32_e32 v11, v11, v27
	v_and_b32_e32 v80, 0xffff0000, v245
	v_mul_f32_e32 v81, 0x3d372713, v80
	v_mul_f32_e32 v81, v81, v80
	v_fma_f32 v81, v81, v80, v80
	v_mul_f32_e32 v81, 0x3fcc422a, v81
	v_mul_f32_e32 v81, 0xbfb8aa3b, v81
	v_exp_f32_e32 v81, v81
	s_nop 0
	v_add_f32_e32 v81, 1.0, v81
	v_rcp_f32_e32 v81, v81
	s_nop 0
	v_mul_f32_e32 v81, v80, v81
	v_mul_f32_e32 v11, v11, v81
	v_add_f32_e32 v12, v12, v28
	v_lshlrev_b32_e32 v80, 16, v246
	v_mul_f32_e32 v81, 0x3d372713, v80
	v_mul_f32_e32 v81, v81, v80
	v_fma_f32 v81, v81, v80, v80
	v_mul_f32_e32 v81, 0x3fcc422a, v81
	v_mul_f32_e32 v81, 0xbfb8aa3b, v81
	v_exp_f32_e32 v81, v81
	s_nop 0
	v_add_f32_e32 v81, 1.0, v81
	v_rcp_f32_e32 v81, v81
	s_nop 0
	v_mul_f32_e32 v81, v80, v81
	v_mul_f32_e32 v12, v12, v81
	v_add_f32_e32 v13, v13, v29
	v_and_b32_e32 v80, 0xffff0000, v246
	v_mul_f32_e32 v81, 0x3d372713, v80
	v_mul_f32_e32 v81, v81, v80
	v_fma_f32 v81, v81, v80, v80
	v_mul_f32_e32 v81, 0x3fcc422a, v81
	v_mul_f32_e32 v81, 0xbfb8aa3b, v81
	v_exp_f32_e32 v81, v81
	s_nop 0
	v_add_f32_e32 v81, 1.0, v81
	v_rcp_f32_e32 v81, v81
	s_nop 0
	v_mul_f32_e32 v81, v80, v81
	v_mul_f32_e32 v13, v13, v81
	v_add_f32_e32 v14, v14, v30
	v_lshlrev_b32_e32 v80, 16, v247
	v_mul_f32_e32 v81, 0x3d372713, v80
	v_mul_f32_e32 v81, v81, v80
	v_fma_f32 v81, v81, v80, v80
	v_mul_f32_e32 v81, 0x3fcc422a, v81
	v_mul_f32_e32 v81, 0xbfb8aa3b, v81
	v_exp_f32_e32 v81, v81
	s_nop 0
	v_add_f32_e32 v81, 1.0, v81
	v_rcp_f32_e32 v81, v81
	s_nop 0
	v_mul_f32_e32 v81, v80, v81
	v_mul_f32_e32 v14, v14, v81
	v_add_f32_e32 v15, v15, v31
	v_and_b32_e32 v80, 0xffff0000, v247
	v_mul_f32_e32 v81, 0x3d372713, v80
	v_mul_f32_e32 v81, v81, v80
	v_fma_f32 v81, v81, v80, v80
	v_mul_f32_e32 v81, 0x3fcc422a, v81
	v_mul_f32_e32 v81, 0xbfb8aa3b, v81
	v_exp_f32_e32 v81, v81
	s_nop 0
	v_add_f32_e32 v81, 1.0, v81
	v_rcp_f32_e32 v81, v81
	s_nop 0
	v_mul_f32_e32 v81, v80, v81
	v_mul_f32_e32 v15, v15, v81
	v_cvt_pk_bf16_f32 v16, v0, v1
	v_cvt_pk_bf16_f32 v17, v2, v3
	v_cvt_pk_bf16_f32 v18, v4, v5
	v_cvt_pk_bf16_f32 v19, v6, v7
	v_cvt_pk_bf16_f32 v20, v8, v9
	v_cvt_pk_bf16_f32 v21, v10, v11
	v_cvt_pk_bf16_f32 v22, v12, v13
	v_cvt_pk_bf16_f32 v23, v14, v15
	global_store_dwordx4 v193, v[16:19], s[0:1]
	global_store_dwordx4 v193, v[20:23], s[0:1] offset:16
	s_waitcnt lgkmcnt(0)
	s_barrier
; template <int PASS>
; __device__ __forceinline__ void lru_tile_phase(const Params& p, int jl, int Mrows, char* smem, int tid, int bid) {
;     ...
;     __syncthreads();
;   }
; }
	s_add_u32 s6, s6, s71
	s_cmp_lt_u32 s6, 0x1100
	s_cbranch_scc1 .Llru2_job
	v_readlane_b32 s36, v255, 11
	v_readlane_b32 s37, v255, 12
	v_readlane_b32 s38, v255, 13
	v_readlane_b32 s39, v255, 14
	v_readlane_b32 s40, v255, 15
	v_readlane_b32 s41, v255, 16
	v_readlane_b32 s42, v255, 17
	v_readlane_b32 s43, v255, 18
	v_readlane_b32 s44, v255, 19
	v_readlane_b32 s45, v255, 20
	v_readlane_b32 s46, v255, 21
	v_readlane_b32 s47, v255, 22
	v_readlane_b32 s48, v255, 23
	v_readlane_b32 s49, v255, 24
	v_readlane_b32 s50, v255, 25
	v_readlane_b32 s51, v255, 26

; template <int PASS>
; __device__ __forceinline__ void lru_tile_phase(const Params& p, int jl, int Mrows, char* smem, int tid, int bid) {
;   char* xcL = smem;
;   float* aL = (float*)(smem + 16384);
;   float* uL = (float*)(smem + 16384 + 65536);
;   const u16* P2 = (const u16*)(p.ws + OFF_S);
;   u16* H = (u16*)(p.ws + OFF_LRU_Y);
;   float2* summ = (float2*)(p.ws + OFF_LRU_SUM);
;   const float* carry = (const float*)(p.ws + OFF_LRU_CAR);
;   const u16* Wbd = (const u16*)(p.ws + OFF_WMIX) + 3072 * 1024;
;   const int ntt = Mrows / 64;
;   bf16x8 wb0[8], wb1[8]; float c_ba = 0.f, c_bx = 0.f, c_sp = 0.f; int n_loaded = -1;
;   for (int job = bid; job < ntt * 8; job += gridDim.x) {
;     asm volatile("" : "+v"(tid));
;     const int lane = tid & 63, wid = tid >> 6, l32 = lane & 31, hi = lane >> 5;
;     const int tt = job >> 3, n = job & 7;
;     const bool lat = tt < 512;
;     const int rowbase = lat ? tt * 64 : ML + (tt - 512) * 64;
;     const int sloc = lat ? (tt & 63) * 64 : ((tt - 512) & 3) * 64;
;     const int TT = lat ? SEQL : CTXL;
;     unsigned gv[16]; float carry_in = 0.f;
;     if (PASS == 2) {
;       const int ch = tid & 127, tg = tid >> 7;
; #pragma unroll
;       for (int i = 0; i < 16; ++i) gv[i] = P2[(size_t)(rowbase + tg * 16 + i) * 2048 + n * 128 + ch];
;       if (tid < 256) carry_in = carry[(size_t)(tt * 2 + (tid >> 7)) * 1024 + n * 128 + (tid & 127)];
;     }
;     {
;       const int ch = tid & 127, tg = tid >> 7, t0 = tg * 16;
;       const int col = n * 128 + ch;
;       float cw0 = p.in[18][(size_t)(jl * 4 + 0) * 1024 + col], cw1 = p.in[18][(size_t)(jl * 4 + 1) * 1024 + col];
;       float cw2 = p.in[18][(size_t)(jl * 4 + 2) * 1024 + col], cw3 = p.in[18][(size_t)(jl * 4 + 3) * 1024 + col];
;       const float cb = p.in[19][(size_t)jl * 1024 + col];
;       float xb[19]; unsigned xraw[19];
;       const u16* xsrc = P2 + (size_t)(rowbase - sloc) * 2048 + 1024 + col;
; #pragma unroll
;       for (int i = 0; i < 19; ++i) {
;         const int s = sloc + t0 + i - 2;
;         const int sc = s < 0 ? 0 : (s >= TT ? TT - 1 : s);
;         xraw[i] = xsrc[(size_t)sc * 2048];
;       }
.LBB0_248:
	s_andn2_b64 vcc, exec, s[0:1]
	s_cbranch_vccnz .LBB0_260
	s_cmpk_gt_i32 s62, 0x10ff
	s_cbranch_scc1 .LBB0_260
	v_readlane_b32 s0, v253, 1
	v_readlane_b32 s1, v253, 2
	s_sub_u32 s0, s0, 0x138
	s_subb_u32 s1, s1, 0
	s_load_dwordx4 s[36:39], s[0:1], 0x90
	s_load_dwordx2 s[40:41], s[0:1], 0xa8
	s_load_dwordx2 s[44:45], s[0:1], 0xb8
	s_load_dwordx2 s[46:47], s[0:1], 0xc0
	s_load_dwordx2 s[42:43], s[0:1], 0xd0
	s_load_dwordx4 s[48:51], s[0:1], 0xe0
	s_load_dwordx2 s[4:5], s[0:1], 0x128
	s_waitcnt lgkmcnt(0)
	s_lshl_b32 s0, s72, 14
	s_add_u32 s36, s36, s0
	s_addc_u32 s37, s37, 0
	s_lshl_b32 s0, s72, 12
	s_add_u32 s38, s38, s0
	s_addc_u32 s39, s39, 0
	s_add_u32 s40, s40, s0
	s_addc_u32 s41, s41, 0
	s_add_u32 s42, s42, s0
	s_addc_u32 s43, s43, 0
	s_add_u32 s44, s44, s0
	s_addc_u32 s45, s45, 0
	s_add_u32 s46, s46, s0
	s_addc_u32 s47, s47, 0
	s_add_u32 s48, s48, s0
	s_addc_u32 s49, s49, 0
	s_add_u32 s50, s50, s0
	s_addc_u32 s51, s51, 0
	s_add_u32 s22, s4, 0x129dc000
	s_addc_u32 s23, s5, 0
	s_add_u32 s24, s4, 0x1325c000
	s_addc_u32 s25, s5, 0
	s_add_u32 s28, s4, 0x1369c000
	s_addc_u32 s29, s5, 0
	s_add_u32 s18, s4, 0x8e00000
	s_addc_u32 s19, s5, 0
	v_and_b32_e32 v80, 63, v203
	v_lshrrev_b32_e32 v81, 6, v203
	v_and_b32_e32 v236, 31, v203
	v_bfe_u32 v237, v203, 5, 1
	v_lshrrev_b32_e32 v84, 4, v203
	v_and_b32_e32 v99, 15, v203
	v_readfirstlane_b32 s0, v81
	s_and_b32 s1, s0, 3
	s_lshr_b32 s16, s0, 2
	s_mov_b32 s27, s0
	v_lshlrev_b32_e32 v190, 1, v84
	v_lshlrev_b32_e32 v191, 4, v99
	v_or_b32_e32 v195, 0, v190
	v_and_b32_e32 v196, 15, v195
	v_xor_b32_e32 v196, v99, v196
	v_lshlrev_b32_e32 v196, 4, v196
	v_lshl_or_b32 v183, v195, 8, v196
	v_or_b32_e32 v195, 1, v190
	v_and_b32_e32 v196, 15, v195
	v_xor_b32_e32 v196, v99, v196
	v_lshlrev_b32_e32 v196, 4, v196
	v_lshl_or_b32 v184, v195, 8, v196
	v_and_b32_e32 v195, 15, v236
	v_xor_b32_e32 v195, v237, v195
	v_lshlrev_b32_e32 v195, 4, v195
	v_lshl_or_b32 v185, v236, 8, v195
	s_lshl_b32 s4, s1, 5
	v_add_u32_e32 v195, s4, v236
	s_lshl_b32 s5, s16, 6
	v_lshl_add_u32 v196, v237, 2, s5
	v_lshlrev_b32_e32 v196, 7, v196
	v_add_u32_e32 v196, v196, v195
	v_lshlrev_b32_e32 v186, 2, v196
	v_add_u32_e32 v186, 0x4000, v186
	v_add_u32_e32 v187, 0x10000, v186
	v_bfe_u32 v196, v236, 3, 1
	v_cmp_eq_u32_e32 vcc, v196, v237
	v_and_b32_e32 v197, 7, v236
	v_lshrrev_b32_e32 v198, 1, v197
	v_and_b32_e32 v197, 1, v197
	v_lshlrev_b32_e32 v197, 4, v197
	v_mov_b32_e32 v199, 0x3f80
	v_lshlrev_b32_e32 v199, v197, v199
	v_cndmask_b32_e32 v199, 0, v199, vcc
	v_lshrrev_b32_e32 v200, 4, v236
	v_cmp_eq_u32_e32 vcc, 0, v200
	v_cmp_eq_u32_e64 s[4:5], 0, v198
	s_and_b64 vcc, vcc, s[4:5]
	v_cndmask_b32_e32 v172, 0, v199, vcc
	v_cmp_eq_u32_e32 vcc, 0, v200
	v_cmp_eq_u32_e64 s[4:5], 1, v198
	s_and_b64 vcc, vcc, s[4:5]
	v_cndmask_b32_e32 v173, 0, v199, vcc
	v_cmp_eq_u32_e32 vcc, 0, v200
	v_cmp_eq_u32_e64 s[4:5], 2, v198
	s_and_b64 vcc, vcc, s[4:5]
	v_cndmask_b32_e32 v174, 0, v199, vcc
	v_cmp_eq_u32_e32 vcc, 0, v200
	v_cmp_eq_u32_e64 s[4:5], 3, v198
	s_and_b64 vcc, vcc, s[4:5]
	v_cndmask_b32_e32 v175, 0, v199, vcc
	v_cmp_eq_u32_e32 vcc, 1, v200
	v_cmp_eq_u32_e64 s[4:5], 0, v198
	s_and_b64 vcc, vcc, s[4:5]
	v_cndmask_b32_e32 v176, 0, v199, vcc
	v_cmp_eq_u32_e32 vcc, 1, v200
	v_cmp_eq_u32_e64 s[4:5], 1, v198
	s_and_b64 vcc, vcc, s[4:5]
	v_cndmask_b32_e32 v177, 0, v199, vcc
	v_cmp_eq_u32_e32 vcc, 1, v200
	v_cmp_eq_u32_e64 s[4:5], 2, v198
	s_and_b64 vcc, vcc, s[4:5]
	v_cndmask_b32_e32 v178, 0, v199, vcc
	v_cmp_eq_u32_e32 vcc, 1, v200
	v_cmp_eq_u32_e64 s[4:5], 3, v198
	s_and_b64 vcc, vcc, s[4:5]
	v_cndmask_b32_e32 v179, 0, v199, vcc
	v_and_b32_e32 v195, 0x7f, v203
	v_bfe_u32 v196, v203, 7, 1
	v_lshl_or_b32 v196, v196, 13, v195
	v_lshlrev_b32_e32 v188, 2, v196
	v_add_u32_e32 v188, 0x4000, v188
	v_bfe_u32 v196, v203, 7, 1
	v_lshl_or_b32 v194, v196, 10, v195
	v_mov_b32_e32 v91, 0xbfb8aa3b
	s_mov_b32 s6, s62
	s_lshr_b32 s10, s6, 3
	s_and_b32 s11, s6, 7
	s_movk_i32 s0, 0x1000
	s_cmp_lt_u32 s10, 512
	s_cselect_b32 s4, 0, 512
	s_cselect_b32 s5, 0, 0x8000
	s_cselect_b32 s1, 63, 3
	s_cselect_b32 s21, s0, 0x100
	s_sub_u32 s0, s10, s4
	s_lshl_b32 s20, s0, 6
	s_add_u32 s20, s20, s5
	s_and_b32 s10, s0, s1
	s_lshl_b32 s10, s10, 6
	s_cmp_eq_u32 s10, 0
	s_cselect_b32 s4, 0, -2
	s_add_u32 s0, s10, 64
	s_cmp_eq_u32 s0, s21
	s_cselect_b32 s5, 63, 0x41
	s_lshl_b32 s0, s20, 12
	s_lshl_b32 s1, s11, 8
	s_add_u32 s0, s0, s1
	s_add_u32 s0, s92, s0
	s_addc_u32 s1, s93, 0
	s_sub_u32 s0, s0, 0x1800
	s_subb_u32 s1, s1, 0
	v_add_u32_e32 v44, -2, v190
	v_max_i32_e32 v49, s4, v44
	v_min_i32_e32 v49, s5, v49
	v_add_u32_e32 v195, 2, v49
	v_lshl_add_u32 v195, v195, 12, v191
	global_load_dwordx4 v[56:59], v195, s[0:1]
	v_add_u32_e32 v45, -1, v190
	v_max_i32_e32 v50, s4, v45
	v_min_i32_e32 v50, s5, v50
	v_add_u32_e32 v195, 2, v50
	v_lshl_add_u32 v195, v195, 12, v191
	global_load_dwordx4 v[60:63], v195, s[0:1]
	v_add_u32_e32 v46, 0, v190
	v_max_i32_e32 v51, s4, v46
	v_min_i32_e32 v51, s5, v51
	v_add_u32_e32 v195, 2, v51
	v_lshl_add_u32 v195, v195, 12, v191
	global_load_dwordx4 v[64:67], v195, s[0:1]
	v_add_u32_e32 v47, 1, v190
	v_max_i32_e32 v52, s4, v47
	v_min_i32_e32 v52, s5, v52
	v_add_u32_e32 v195, 2, v52
	v_lshl_add_u32 v195, v195, 12, v191
	global_load_dwordx4 v[68:71], v195, s[0:1]
	v_add_u32_e32 v48, 2, v190
	v_max_i32_e32 v53, s4, v48
	v_min_i32_e32 v53, s5, v53
	v_add_u32_e32 v195, 2, v53
	v_lshl_add_u32 v195, v195, 12, v191
	global_load_dwordx4 v[72:75], v195, s[0:1]
	s_mov_b32 s26, -1

; __device__ __forceinline__ u16 f2bf(float x) { return (u16)(cvtpk(x, 0.f) & 0xffffu); }
; template <int PASS>
; __device__ __forceinline__ void lru_tile_phase(const Params& p, int jl, int Mrows, char* smem, int tid, int bid) {
;     ...
;     {
;       const int ch = tid & 127, tg = tid >> 7, t0 = tg * 16;
;       const int col = n * 128 + ch;
;       float cw0 = p.in[18][(size_t)(jl * 4 + 0) * 1024 + col], cw1 = p.in[18][(size_t)(jl * 4 + 1) * 1024 + col];
;       float cw2 = p.in[18][(size_t)(jl * 4 + 2) * 1024 + col], cw3 = p.in[18][(size_t)(jl * 4 + 3) * 1024 + col];
;       const float cb = p.in[19][(size_t)jl * 1024 + col];
;       float xb[19]; unsigned xraw[19];
;       const u16* xsrc = P2 + (size_t)(rowbase - sloc) * 2048 + 1024 + col;
; #pragma unroll
;       for (int i = 0; i < 19; ++i) {
;         const int s = sloc + t0 + i - 2;
;         const int sc = s < 0 ? 0 : (s >= TT ? TT - 1 : s);
;         xraw[i] = xsrc[(size_t)sc * 2048];
;       }
; #pragma unroll
;       for (int i = 0; i < 19; ++i) {
;         const int s = sloc + t0 + i - 2;
;         xb[i] = (s >= 0 && s < TT) ? __uint_as_float(xraw[i] << 16) : 0.f;
;       }
; #pragma unroll
;       for (int i = 0; i < 16; ++i) {
;         const float xc = cb + cw0 * xb[i] + cw1 * xb[i + 1] + cw2 * xb[i + 2] + cw3 * xb[i + 3];
;         *(u16*)(xcL + swz256(t0 + i, ch >> 3) + (ch & 7) * 2) = f2bf(xc);
;       }
;     }
.Llru1_nloaded:
	s_movk_i32 s0, 0x1000
	s_cmp_lt_u32 s8, 512
	s_cselect_b32 s4, 0, 512
	s_cselect_b32 s5, 0, 0x8000
	s_cselect_b32 s1, 63, 3
	s_cselect_b32 s11, s0, 0x100
	s_sub_u32 s0, s8, s4
	s_lshl_b32 s9, s0, 6
	s_add_u32 s9, s9, s5
	s_and_b32 s10, s0, s1
	s_lshl_b32 s10, s10, 6
	s_cmp_eq_u32 s10, 0
	s_cselect_b32 s4, 0, -2
	s_add_u32 s0, s10, 64
	s_cmp_eq_u32 s0, s11
	s_cselect_b32 s5, 63, 0x41
	s_lshl_b32 s0, s9, 12
	s_lshl_b32 s1, s7, 8
	s_add_u32 s0, s0, s1
	s_add_u32 s20, s92, s0
	s_addc_u32 s21, s93, 0
	s_sub_u32 s0, s20, 0x1800
	s_subb_u32 s1, s21, 0
	v_mov_b32_e32 v20, v132
	v_mov_b32_e32 v21, v133
	v_mov_b32_e32 v22, v134
	v_mov_b32_e32 v23, v135
	v_mov_b32_e32 v24, v136
	v_mov_b32_e32 v25, v137
	v_mov_b32_e32 v26, v138
	v_mov_b32_e32 v27, v139
	v_mov_b32_e32 v28, v132
	v_mov_b32_e32 v29, v133
	v_mov_b32_e32 v30, v134
	v_mov_b32_e32 v31, v135
	v_mov_b32_e32 v32, v136
	v_mov_b32_e32 v33, v137
	v_mov_b32_e32 v34, v138
	v_mov_b32_e32 v35, v139
	s_cmp_gt_u32 s27, 3
	s_cbranch_scc1 .Llru1_cv0a
	s_waitcnt vmcnt(5)
	s_branch .Llru1_cv0b
.Llru1_cv0a:
	s_waitcnt vmcnt(4)
.Llru1_cv0b:
	v_cmp_eq_u32_e32 vcc, v44, v49
	s_nop 1
	v_cndmask_b32_e32 v56, 0, v56, vcc
	v_cndmask_b32_e32 v57, 0, v57, vcc
	v_cndmask_b32_e32 v58, 0, v58, vcc
	v_cndmask_b32_e32 v59, 0, v59, vcc
	v_lshlrev_b32_e32 v36, 16, v56
	v_and_b32_e32 v37, 0xffff0000, v56
	v_lshlrev_b32_e32 v38, 16, v57
	v_and_b32_e32 v39, 0xffff0000, v57
	v_lshlrev_b32_e32 v40, 16, v58
	v_and_b32_e32 v41, 0xffff0000, v58
	v_lshlrev_b32_e32 v42, 16, v59
	v_and_b32_e32 v43, 0xffff0000, v59
	v_fmac_f32_e32 v20, v100, v36
	v_fmac_f32_e32 v21, v101, v37
	v_fmac_f32_e32 v22, v102, v38
	v_fmac_f32_e32 v23, v103, v39
	v_fmac_f32_e32 v24, v104, v40
	v_fmac_f32_e32 v25, v105, v41
	v_fmac_f32_e32 v26, v106, v42
	v_fmac_f32_e32 v27, v107, v43
	s_cmp_gt_u32 s27, 3
	s_cbranch_scc1 .Llru1_cv1a
	s_waitcnt vmcnt(4)
	s_branch .Llru1_cv1b
.Llru1_cv1a:
	s_waitcnt vmcnt(3)
.Llru1_cv1b:
	v_cmp_eq_u32_e32 vcc, v45, v50
	s_nop 1
	v_cndmask_b32_e32 v60, 0, v60, vcc
	v_cndmask_b32_e32 v61, 0, v61, vcc
	v_cndmask_b32_e32 v62, 0, v62, vcc
	v_cndmask_b32_e32 v63, 0, v63, vcc
	v_lshlrev_b32_e32 v36, 16, v60
	v_and_b32_e32 v37, 0xffff0000, v60
	v_lshlrev_b32_e32 v38, 16, v61
	v_and_b32_e32 v39, 0xffff0000, v61
	v_lshlrev_b32_e32 v40, 16, v62
	v_and_b32_e32 v41, 0xffff0000, v62
	v_lshlrev_b32_e32 v42, 16, v63
	v_and_b32_e32 v43, 0xffff0000, v63
	v_fmac_f32_e32 v20, v108, v36
	v_fmac_f32_e32 v21, v109, v37
	v_fmac_f32_e32 v22, v110, v38
	v_fmac_f32_e32 v23, v111, v39
	v_fmac_f32_e32 v24, v112, v40
	v_fmac_f32_e32 v25, v113, v41
	v_fmac_f32_e32 v26, v114, v42
	v_fmac_f32_e32 v27, v115, v43
	v_fmac_f32_e32 v28, v100, v36
	v_fmac_f32_e32 v29, v101, v37
	v_fmac_f32_e32 v30, v102, v38
	v_fmac_f32_e32 v31, v103, v39
	v_fmac_f32_e32 v32, v104, v40
	v_fmac_f32_e32 v33, v105, v41
	v_fmac_f32_e32 v34, v106, v42
	v_fmac_f32_e32 v35, v107, v43
	s_cmp_gt_u32 s27, 3
	s_cbranch_scc1 .Llru1_cv2a
	s_waitcnt vmcnt(3)
	s_branch .Llru1_cv2b
.Llru1_cv2a:
	s_waitcnt vmcnt(2)
.Llru1_cv2b:
	v_cmp_eq_u32_e32 vcc, v46, v51
	s_nop 1
	v_cndmask_b32_e32 v64, 0, v64, vcc
	v_cndmask_b32_e32 v65, 0, v65, vcc
	v_cndmask_b32_e32 v66, 0, v66, vcc
	v_cndmask_b32_e32 v67, 0, v67, vcc
	v_lshlrev_b32_e32 v36, 16, v64
	v_and_b32_e32 v37, 0xffff0000, v64
	v_lshlrev_b32_e32 v38, 16, v65
	v_and_b32_e32 v39, 0xffff0000, v65
	v_lshlrev_b32_e32 v40, 16, v66
	v_and_b32_e32 v41, 0xffff0000, v66
	v_lshlrev_b32_e32 v42, 16, v67
	v_and_b32_e32 v43, 0xffff0000, v67
	v_fmac_f32_e32 v20, v116, v36
	v_fmac_f32_e32 v21, v117, v37
	v_fmac_f32_e32 v22, v118, v38
	v_fmac_f32_e32 v23, v119, v39
	v_fmac_f32_e32 v24, v120, v40
	v_fmac_f32_e32 v25, v121, v41
	v_fmac_f32_e32 v26, v122, v42
	v_fmac_f32_e32 v27, v123, v43
	v_fmac_f32_e32 v28, v108, v36
	v_fmac_f32_e32 v29, v109, v37
	v_fmac_f32_e32 v30, v110, v38
	v_fmac_f32_e32 v31, v111, v39
	v_fmac_f32_e32 v32, v112, v40
	v_fmac_f32_e32 v33, v113, v41
	v_fmac_f32_e32 v34, v114, v42
	v_fmac_f32_e32 v35, v115, v43
	s_cmp_gt_u32 s27, 3
	s_cbranch_scc1 .Llru1_cv3a
	s_waitcnt vmcnt(2)
	s_branch .Llru1_cv3b

; __device__ __forceinline__ u16 f2bf(float x) { return (u16)(cvtpk(x, 0.f) & 0xffffu); }
; template <int PASS>
; __device__ __forceinline__ void lru_tile_phase(const Params& p, int jl, int Mrows, char* smem, int tid, int bid) {
;     ...
;       for (int i = 0; i < 19; ++i) {
;         const int s = sloc + t0 + i - 2;
;         xb[i] = (s >= 0 && s < TT) ? __uint_as_float(xraw[i] << 16) : 0.f;
;       }
; #pragma unroll
;       for (int i = 0; i < 16; ++i) {
;         const float xc = cb + cw0 * xb[i] + cw1 * xb[i + 1] + cw2 * xb[i + 2] + cw3 * xb[i + 3];
;         *(u16*)(xcL + swz256(t0 + i, ch >> 3) + (ch & 7) * 2) = f2bf(xc);
;       }
.Llru1_cv3b:
	v_cmp_eq_u32_e32 vcc, v47, v52
	s_nop 1
	v_cndmask_b32_e32 v68, 0, v68, vcc
	v_cndmask_b32_e32 v69, 0, v69, vcc
	v_cndmask_b32_e32 v70, 0, v70, vcc
	v_cndmask_b32_e32 v71, 0, v71, vcc
	v_lshlrev_b32_e32 v36, 16, v68
	v_and_b32_e32 v37, 0xffff0000, v68
	v_lshlrev_b32_e32 v38, 16, v69
	v_and_b32_e32 v39, 0xffff0000, v69
	v_lshlrev_b32_e32 v40, 16, v70
	v_and_b32_e32 v41, 0xffff0000, v70
	v_lshlrev_b32_e32 v42, 16, v71
	v_and_b32_e32 v43, 0xffff0000, v71
	v_fmac_f32_e32 v20, v124, v36
	v_fmac_f32_e32 v21, v125, v37
	v_fmac_f32_e32 v22, v126, v38
	v_fmac_f32_e32 v23, v127, v39
	v_fmac_f32_e32 v24, v128, v40
	v_fmac_f32_e32 v25, v129, v41
	v_fmac_f32_e32 v26, v130, v42
	v_fmac_f32_e32 v27, v131, v43
	v_fmac_f32_e32 v28, v116, v36
	v_fmac_f32_e32 v29, v117, v37
	v_fmac_f32_e32 v30, v118, v38
	v_fmac_f32_e32 v31, v119, v39
	v_fmac_f32_e32 v32, v120, v40
	v_fmac_f32_e32 v33, v121, v41
	v_fmac_f32_e32 v34, v122, v42
	v_fmac_f32_e32 v35, v123, v43
	s_cmp_gt_u32 s27, 3
	s_cbranch_scc1 .Llru1_cv4a
	s_waitcnt vmcnt(1)
	s_branch .Llru1_cv4b

; __device__ __forceinline__ u16 f2bf(float x) { return (u16)(cvtpk(x, 0.f) & 0xffffu); }
; __device__ __forceinline__ float fexp(float x) { return __builtin_amdgcn_exp2f(x * 1.4426950408889634f); }
; __device__ __forceinline__ float flog(float x) { return __builtin_amdgcn_logf(x) * 0.6931471805599453f; }
; template <int PASS>
; __device__ __forceinline__ void lru_tile_phase(const Params& p, int jl, int Mrows, char* smem, int tid, int bid) {
;     ...
; #pragma unroll
;       for (int i = 0; i < 16; ++i) {
;         const float xc = cb + cw0 * xb[i] + cw1 * xb[i + 1] + cw2 * xb[i + 2] + cw3 * xb[i + 3];
;         *(u16*)(xcL + swz256(t0 + i, ch >> 3) + (ch & 7) * 2) = f2bf(xc);
;       }
;     }
;     __syncthreads();
;     {
;       const int cbk = wid & 3, dh = wid >> 2;
;       const int chl = cbk * 32 + l32, col = n * 128 + chl;
;       if (n != n_loaded) {
;         const u16* wbase = Wbd + (size_t)n * 16384 + (size_t)chl * 128 + hi * 8;
; #pragma unroll
;         for (int k16 = 0; k16 < 8; ++k16) {
;           wb0[k16] = *(const bf16x8*)(wbase + (size_t)(dh * 2 + 0) * 131072 + k16 * 16);
;           wb1[k16] = *(const bf16x8*)(wbase + (size_t)(dh * 2 + 1) * 131072 + k16 * 16);
;         }
;         const float* pba = dh ? p.in[26] : p.in[21]; const float* pbx = dh ? p.in[28] : p.in[23]; const float* plam = dh ? p.in[29] : p.in[24];
;         c_ba = pba[(size_t)jl * 1024 + col]; c_bx = pbx[(size_t)jl * 1024 + col];
;         c_sp = -8.f * flog(1.f + fexp(-plam[(size_t)jl * 1024 + col]));
;         n_loaded = n;
;       }
; #pragma unroll
;       for (int tb = 0; tb < 2; ++tb) {
;         f32x16 acc0, acc1;
; #pragma unroll
;         for (int r = 0; r < 16; ++r) { acc0[r] = 0.f; acc1[r] = 0.f; }
;         bf16x8 af[8];
; #pragma unroll
;         for (int k16 = 0; k16 < 8; ++k16) af[k16] = *(const bf16x8*)(xcL + swz256(tb * 32 + l32, k16 * 2 + hi));
; #pragma unroll
;         for (int k16 = 0; k16 < 8; ++k16) {
;           acc0 = __builtin_amdgcn_mfma_f32_32x32x16_bf16(af[k16], wb0[k16], acc0, 0, 0, 0);
;           acc1 = __builtin_amdgcn_mfma_f32_32x32x16_bf16(af[k16], wb1[k16], acc1, 0, 0, 0);
;         }
.Llru1_cv4b:
	v_cmp_eq_u32_e32 vcc, v48, v53
	s_nop 1
	v_cndmask_b32_e32 v72, 0, v72, vcc
	v_cndmask_b32_e32 v73, 0, v73, vcc
	v_cndmask_b32_e32 v74, 0, v74, vcc
	v_cndmask_b32_e32 v75, 0, v75, vcc
	v_lshlrev_b32_e32 v36, 16, v72
	v_and_b32_e32 v37, 0xffff0000, v72
	v_lshlrev_b32_e32 v38, 16, v73
	v_and_b32_e32 v39, 0xffff0000, v73
	v_lshlrev_b32_e32 v40, 16, v74
	v_and_b32_e32 v41, 0xffff0000, v74
	v_lshlrev_b32_e32 v42, 16, v75
	v_and_b32_e32 v43, 0xffff0000, v75
	v_fmac_f32_e32 v28, v124, v36
	v_fmac_f32_e32 v29, v125, v37
	v_fmac_f32_e32 v30, v126, v38
	v_fmac_f32_e32 v31, v127, v39
	v_fmac_f32_e32 v32, v128, v40
	v_fmac_f32_e32 v33, v129, v41
	v_fmac_f32_e32 v34, v130, v42
	v_fmac_f32_e32 v35, v131, v43
	v_cvt_pk_bf16_f32 v36, v20, v21
	v_cvt_pk_bf16_f32 v37, v22, v23
	v_cvt_pk_bf16_f32 v38, v24, v25
	v_cvt_pk_bf16_f32 v39, v26, v27
	v_cvt_pk_bf16_f32 v40, v28, v29
	v_cvt_pk_bf16_f32 v41, v30, v31
	v_cvt_pk_bf16_f32 v42, v32, v33
	v_cvt_pk_bf16_f32 v43, v34, v35
	ds_write_b128 v183, v[36:39]
	ds_write_b128 v184, v[40:43]
	s_waitcnt lgkmcnt(0)
	s_barrier
	ds_read_b128 v[48:51], v185 offset:0
	v_xor_b32_e32 v196, 32, v185
	ds_read_b128 v[52:55], v196 offset:0
	v_xor_b32_e32 v195, 64, v185
	ds_read_b128 v[56:59], v195 offset:0
	v_xor_b32_e32 v196, 96, v185
	ds_read_b128 v[60:63], v196 offset:0
	v_xor_b32_e32 v195, 128, v185
	ds_read_b128 v[64:67], v195 offset:0
	v_xor_b32_e32 v196, 160, v185
	ds_read_b128 v[68:71], v196 offset:0
	v_xor_b32_e32 v195, 192, v185
	ds_read_b128 v[72:75], v195 offset:0
	v_xor_b32_e32 v196, 224, v185
	ds_read_b128 v[76:79], v196 offset:0
	s_waitcnt lgkmcnt(7)
	v_mfma_f32_32x32x16_bf16 v[0:15], v[48:51], v[140:143], 0
	v_mfma_f32_32x32x16_bf16 v[16:31], v[48:51], v[204:207], 0
	s_waitcnt lgkmcnt(6)
	v_mfma_f32_32x32x16_bf16 v[0:15], v[52:55], v[144:147], v[0:15]
	v_mfma_f32_32x32x16_bf16 v[16:31], v[52:55], v[208:211], v[16:31]
	s_waitcnt lgkmcnt(5)
	v_mfma_f32_32x32x16_bf16 v[0:15], v[56:59], v[148:151], v[0:15]
	v_mfma_f32_32x32x16_bf16 v[16:31], v[56:59], v[212:215], v[16:31]
	s_waitcnt lgkmcnt(4)
	v_mfma_f32_32x32x16_bf16 v[0:15], v[60:63], v[152:155], v[0:15]
	v_mfma_f32_32x32x16_bf16 v[16:31], v[60:63], v[216:219], v[16:31]
	s_waitcnt lgkmcnt(3)
	v_mfma_f32_32x32x16_bf16 v[0:15], v[64:67], v[156:159], v[0:15]
	v_mfma_f32_32x32x16_bf16 v[16:31], v[64:67], v[220:223], v[16:31]
	s_waitcnt lgkmcnt(2)
	v_mfma_f32_32x32x16_bf16 v[0:15], v[68:71], v[160:163], v[0:15]
	v_mfma_f32_32x32x16_bf16 v[16:31], v[68:71], v[224:227], v[16:31]
	s_waitcnt lgkmcnt(1)
	v_mfma_f32_32x32x16_bf16 v[0:15], v[72:75], v[164:167], v[0:15]
	v_mfma_f32_32x32x16_bf16 v[16:31], v[72:75], v[228:231], v[16:31]
	s_waitcnt lgkmcnt(0)
	v_mfma_f32_32x32x16_bf16 v[0:15], v[76:79], v[168:171], v[0:15]
	v_mfma_f32_32x32x16_bf16 v[16:31], v[76:79], v[232:235], v[16:31]
	s_and_b32 s0, s27, 3
	s_cmp_eq_u32 s0, 0
	s_cbranch_scc0 .Llru1_id0_0
	v_mfma_f32_32x32x16_bf16 v[32:47], v[48:51], v[172:175], 0
	v_mfma_f32_32x32x16_bf16 v[32:47], v[52:55], v[176:179], v[32:47]

; template <int PASS>
; __device__ __forceinline__ void lru_tile_phase(const Params& p, int jl, int Mrows, char* smem, int tid, int bid) {
;     ...
;     if (tid < 256) {
;       const int dir = tid >> 7, ch = tid & 127;
;       const size_t sidx = (size_t)(tt * 2 + dir) * 1024 + n * 128 + ch;
;       float hst = 0.f, ap = 1.f;
;       if (PASS == 2) hst = carry_in;
;       const float* ap_ = aL + (dir * 64) * 128 + ch;
;       float* up_ = uL + (dir * 64) * 128 + ch;
; #pragma unroll 1
;       for (int i0 = 0; i0 < 64; i0 += 16) {
;         float av[16], uv[16];
; #pragma unroll
;         for (int k = 0; k < 16; ++k) { const int t = dir ? 63 - (i0 + k) : i0 + k; av[k] = ap_[t * 128]; uv[k] = up_[t * 128]; }
; #pragma unroll
;         for (int k = 0; k < 16; ++k) { hst = fmaf(av[k], hst, uv[k]); if (PASS == 1) ap *= av[k]; else uv[k] = hst; }
.Llru1_pfdone:
	s_cmp_gt_u32 s27, 3
	s_cbranch_scc1 .Llru1_scan_done
	v_mov_b32_e32 v96, 0
	v_mov_b32_e32 v97, 1.0
	v_add_u32_e32 v195, 0x10000, v188
	s_cmp_gt_u32 s27, 1
	s_cbranch_scc1 .Llru1_scan_bwd
	ds_read2st64_b32 v[0:1], v188 offset0:0 offset1:2
	ds_read2st64_b32 v[2:3], v188 offset0:4 offset1:6
	ds_read2st64_b32 v[4:5], v188 offset0:8 offset1:10
	ds_read2st64_b32 v[6:7], v188 offset0:12 offset1:14
	ds_read2st64_b32 v[8:9], v195 offset0:0 offset1:2
	ds_read2st64_b32 v[10:11], v195 offset0:4 offset1:6
	ds_read2st64_b32 v[12:13], v195 offset0:8 offset1:10
	ds_read2st64_b32 v[14:15], v195 offset0:12 offset1:14
	s_waitcnt lgkmcnt(0)
	ds_read2st64_b32 v[16:17], v188 offset0:16 offset1:18
	ds_read2st64_b32 v[18:19], v188 offset0:20 offset1:22
	ds_read2st64_b32 v[20:21], v188 offset0:24 offset1:26
	ds_read2st64_b32 v[22:23], v188 offset0:28 offset1:30
	ds_read2st64_b32 v[24:25], v195 offset0:16 offset1:18
	ds_read2st64_b32 v[26:27], v195 offset0:20 offset1:22
	ds_read2st64_b32 v[28:29], v195 offset0:24 offset1:26
	ds_read2st64_b32 v[30:31], v195 offset0:28 offset1:30
	v_fma_f32 v96, v0, v96, v8
	v_mul_f32_e32 v97, v97, v0
	v_fma_f32 v96, v1, v96, v9
	v_mul_f32_e32 v97, v97, v1
	v_fma_f32 v96, v2, v96, v10
	v_mul_f32_e32 v97, v97, v2
	v_fma_f32 v96, v3, v96, v11
	v_mul_f32_e32 v97, v97, v3
	v_fma_f32 v96, v4, v96, v12
	v_mul_f32_e32 v97, v97, v4
	v_fma_f32 v96, v5, v96, v13
	v_mul_f32_e32 v97, v97, v5
	v_fma_f32 v96, v6, v96, v14
	v_mul_f32_e32 v97, v97, v6
	v_fma_f32 v96, v7, v96, v15
	v_mul_f32_e32 v97, v97, v7
	s_waitcnt lgkmcnt(0)
	ds_read2st64_b32 v[0:1], v188 offset0:32 offset1:34
	ds_read2st64_b32 v[2:3], v188 offset0:36 offset1:38
	ds_read2st64_b32 v[4:5], v188 offset0:40 offset1:42
	ds_read2st64_b32 v[6:7], v188 offset0:44 offset1:46
	ds_read2st64_b32 v[8:9], v195 offset0:32 offset1:34
	ds_read2st64_b32 v[10:11], v195 offset0:36 offset1:38
	ds_read2st64_b32 v[12:13], v195 offset0:40 offset1:42
	ds_read2st64_b32 v[14:15], v195 offset0:44 offset1:46
	v_fma_f32 v96, v16, v96, v24
	v_mul_f32_e32 v97, v97, v16
	v_fma_f32 v96, v17, v96, v25
	v_mul_f32_e32 v97, v97, v17
	v_fma_f32 v96, v18, v96, v26
	v_mul_f32_e32 v97, v97, v18
	v_fma_f32 v96, v19, v96, v27
	v_mul_f32_e32 v97, v97, v19
	v_fma_f32 v96, v20, v96, v28
	v_mul_f32_e32 v97, v97, v20
	v_fma_f32 v96, v21, v96, v29
	v_mul_f32_e32 v97, v97, v21
	v_fma_f32 v96, v22, v96, v30
	v_mul_f32_e32 v97, v97, v22
	v_fma_f32 v96, v23, v96, v31
	v_mul_f32_e32 v97, v97, v23
	s_waitcnt lgkmcnt(0)
	ds_read2st64_b32 v[16:17], v188 offset0:48 offset1:50
	ds_read2st64_b32 v[18:19], v188 offset0:52 offset1:54
	ds_read2st64_b32 v[20:21], v188 offset0:56 offset1:58
	ds_read2st64_b32 v[22:23], v188 offset0:60 offset1:62
	ds_read2st64_b32 v[24:25], v195 offset0:48 offset1:50
	ds_read2st64_b32 v[26:27], v195 offset0:52 offset1:54
	ds_read2st64_b32 v[28:29], v195 offset0:56 offset1:58
	ds_read2st64_b32 v[30:31], v195 offset0:60 offset1:62
	v_fma_f32 v96, v0, v96, v8
	v_mul_f32_e32 v97, v97, v0
	v_fma_f32 v96, v1, v96, v9
	v_mul_f32_e32 v97, v97, v1
	v_fma_f32 v96, v2, v96, v10
	v_mul_f32_e32 v97, v97, v2
	v_fma_f32 v96, v3, v96, v11
	v_mul_f32_e32 v97, v97, v3
	v_fma_f32 v96, v4, v96, v12
	v_mul_f32_e32 v97, v97, v4
	v_fma_f32 v96, v5, v96, v13
	v_mul_f32_e32 v97, v97, v5
	v_fma_f32 v96, v6, v96, v14
	v_mul_f32_e32 v97, v97, v6
	v_fma_f32 v96, v7, v96, v15
	v_mul_f32_e32 v97, v97, v7
	s_waitcnt lgkmcnt(0)
; template <int PASS>
; __device__ __forceinline__ void lru_tile_phase(const Params& p, int jl, int Mrows, char* smem, int tid, int bid) {
;     ...
; #pragma unroll 1
;       for (int i0 = 0; i0 < 64; i0 += 16) {
;         float av[16], uv[16];
; #pragma unroll
;         for (int k = 0; k < 16; ++k) { const int t = dir ? 63 - (i0 + k) : i0 + k; av[k] = ap_[t * 128]; uv[k] = up_[t * 128]; }
; #pragma unroll
;         for (int k = 0; k < 16; ++k) { hst = fmaf(av[k], hst, uv[k]); if (PASS == 1) ap *= av[k]; else uv[k] = hst; }
;         if (PASS == 2) {
; #pragma unroll
;           for (int k = 0; k < 16; ++k) { const int t = dir ? 63 - (i0 + k) : i0 + k; up_[t * 128] = uv[k]; }
;         }
;       }
;       if (PASS == 1) summ[sidx] = make_float2(ap, hst);
	ds_read2st64_b32 v[0:1], v188 offset0:64 offset1:66
	ds_read2st64_b32 v[2:3], v188 offset0:68 offset1:70
	ds_read2st64_b32 v[4:5], v188 offset0:72 offset1:74
	ds_read2st64_b32 v[6:7], v188 offset0:76 offset1:78
	ds_read2st64_b32 v[8:9], v195 offset0:64 offset1:66
	ds_read2st64_b32 v[10:11], v195 offset0:68 offset1:70
	ds_read2st64_b32 v[12:13], v195 offset0:72 offset1:74
	ds_read2st64_b32 v[14:15], v195 offset0:76 offset1:78
	v_fma_f32 v96, v16, v96, v24
	v_mul_f32_e32 v97, v97, v16
	v_fma_f32 v96, v17, v96, v25
	v_mul_f32_e32 v97, v97, v17
	v_fma_f32 v96, v18, v96, v26
	v_mul_f32_e32 v97, v97, v18
	v_fma_f32 v96, v19, v96, v27
	v_mul_f32_e32 v97, v97, v19
	v_fma_f32 v96, v20, v96, v28
	v_mul_f32_e32 v97, v97, v20
	v_fma_f32 v96, v21, v96, v29
	v_mul_f32_e32 v97, v97, v21
	v_fma_f32 v96, v22, v96, v30
	v_mul_f32_e32 v97, v97, v22
	v_fma_f32 v96, v23, v96, v31
	v_mul_f32_e32 v97, v97, v23
	s_waitcnt lgkmcnt(0)
	ds_read2st64_b32 v[16:17], v188 offset0:80 offset1:82
	ds_read2st64_b32 v[18:19], v188 offset0:84 offset1:86
	ds_read2st64_b32 v[20:21], v188 offset0:88 offset1:90
	ds_read2st64_b32 v[22:23], v188 offset0:92 offset1:94
	ds_read2st64_b32 v[24:25], v195 offset0:80 offset1:82
	ds_read2st64_b32 v[26:27], v195 offset0:84 offset1:86
	ds_read2st64_b32 v[28:29], v195 offset0:88 offset1:90
	ds_read2st64_b32 v[30:31], v195 offset0:92 offset1:94
	v_fma_f32 v96, v0, v96, v8
	v_mul_f32_e32 v97, v97, v0
	v_fma_f32 v96, v1, v96, v9
	v_mul_f32_e32 v97, v97, v1
	v_fma_f32 v96, v2, v96, v10
	v_mul_f32_e32 v97, v97, v2
	v_fma_f32 v96, v3, v96, v11
	v_mul_f32_e32 v97, v97, v3
	v_fma_f32 v96, v4, v96, v12
	v_mul_f32_e32 v97, v97, v4
	v_fma_f32 v96, v5, v96, v13
	v_mul_f32_e32 v97, v97, v5
	v_fma_f32 v96, v6, v96, v14
	v_mul_f32_e32 v97, v97, v6
	v_fma_f32 v96, v7, v96, v15
	v_mul_f32_e32 v97, v97, v7
	s_waitcnt lgkmcnt(0)
	ds_read2st64_b32 v[0:1], v188 offset0:96 offset1:98
	ds_read2st64_b32 v[2:3], v188 offset0:100 offset1:102
	ds_read2st64_b32 v[4:5], v188 offset0:104 offset1:106
	ds_read2st64_b32 v[6:7], v188 offset0:108 offset1:110
	ds_read2st64_b32 v[8:9], v195 offset0:96 offset1:98
	ds_read2st64_b32 v[10:11], v195 offset0:100 offset1:102
	ds_read2st64_b32 v[12:13], v195 offset0:104 offset1:106
	ds_read2st64_b32 v[14:15], v195 offset0:108 offset1:110
	v_fma_f32 v96, v16, v96, v24
	v_mul_f32_e32 v97, v97, v16
	v_fma_f32 v96, v17, v96, v25
	v_mul_f32_e32 v97, v97, v17
	v_fma_f32 v96, v18, v96, v26
	v_mul_f32_e32 v97, v97, v18
	v_fma_f32 v96, v19, v96, v27
	v_mul_f32_e32 v97, v97, v19
	v_fma_f32 v96, v20, v96, v28
	v_mul_f32_e32 v97, v97, v20
	v_fma_f32 v96, v21, v96, v29
	v_mul_f32_e32 v97, v97, v21
	v_fma_f32 v96, v22, v96, v30
	v_mul_f32_e32 v97, v97, v22
	v_fma_f32 v96, v23, v96, v31
	v_mul_f32_e32 v97, v97, v23
	s_waitcnt lgkmcnt(0)
	ds_read2st64_b32 v[16:17], v188 offset0:112 offset1:114
	ds_read2st64_b32 v[18:19], v188 offset0:116 offset1:118
	ds_read2st64_b32 v[20:21], v188 offset0:120 offset1:122
	ds_read2st64_b32 v[22:23], v188 offset0:124 offset1:126
	ds_read2st64_b32 v[24:25], v195 offset0:112 offset1:114
	ds_read2st64_b32 v[26:27], v195 offset0:116 offset1:118
	ds_read2st64_b32 v[28:29], v195 offset0:120 offset1:122
	ds_read2st64_b32 v[30:31], v195 offset0:124 offset1:126
	v_fma_f32 v96, v0, v96, v8
	v_mul_f32_e32 v97, v97, v0
	v_fma_f32 v96, v1, v96, v9
	v_mul_f32_e32 v97, v97, v1
	v_fma_f32 v96, v2, v96, v10
	v_mul_f32_e32 v97, v97, v2
	v_fma_f32 v96, v3, v96, v11
	v_mul_f32_e32 v97, v97, v3
	v_fma_f32 v96, v4, v96, v12
	v_mul_f32_e32 v97, v97, v4
	v_fma_f32 v96, v5, v96, v13
	v_mul_f32_e32 v97, v97, v5
	v_fma_f32 v96, v6, v96, v14
	v_mul_f32_e32 v97, v97, v6
	v_fma_f32 v96, v7, v96, v15
	v_mul_f32_e32 v97, v97, v7
	s_waitcnt lgkmcnt(0)
	v_fma_f32 v96, v16, v96, v24
	v_mul_f32_e32 v97, v97, v16
	v_fma_f32 v96, v17, v96, v25
	v_mul_f32_e32 v97, v97, v17
	v_fma_f32 v96, v18, v96, v26
	v_mul_f32_e32 v97, v97, v18
	v_fma_f32 v96, v19, v96, v27
	v_mul_f32_e32 v97, v97, v19
	v_fma_f32 v96, v20, v96, v28
	v_mul_f32_e32 v97, v97, v20
	v_fma_f32 v96, v21, v96, v29
	v_mul_f32_e32 v97, v97, v21
	v_fma_f32 v96, v22, v96, v30
	v_mul_f32_e32 v97, v97, v22
	v_fma_f32 v96, v23, v96, v31
	v_mul_f32_e32 v97, v97, v23
	s_branch .Llru1_scan_store

; __device__ __forceinline__ u16 f2bf(float x) { return (u16)(cvtpk(x, 0.f) & 0xffffu); }
; __device__ __forceinline__ float fexp(float x) { return __builtin_amdgcn_exp2f(x * 1.4426950408889634f); }
; template <int PASS>
; __device__ __forceinline__ void lru_tile_phase(const Params& p, int jl, int Mrows, char* smem, int tid, int bid) {
;     ...
;       if (PASS == 1) summ[sidx] = make_float2(ap, hst);
;     }
;     if (PASS == 2) {
;       __syncthreads();
;       const int ch = tid & 127, tg = tid >> 7;
;       const int col = n * 128 + ch;
;       float hsv[16];
; #pragma unroll
;       for (int i = 0; i < 16; ++i) { const int t = tg * 16 + i; hsv[i] = uL[(0 * 64 + t) * 128 + ch] + uL[(1 * 64 + t) * 128 + ch]; }
; #pragma unroll
;       for (int i = 0; i < 16; ++i) {
;         const int t = tg * 16 + i;
;         const float hs = hsv[i];
;         const float gt = __uint_as_float(gv[i] << 16);
;         const float z2 = 1.5957691216057308f * (gt + 0.044715f * gt * gt * gt);
;         const float gl = gt * __builtin_amdgcn_rcpf(1.f + fexp(-z2));
;         H[(size_t)(rowbase + t) * 1024 + col] = f2bf(hs * gl);
;       }
;     }
;     __syncthreads();
;   }
.Llru1_scan_done:
	s_waitcnt lgkmcnt(0)
	s_barrier
	s_add_u32 s6, s6, s71
	s_cmp_lt_u32 s6, 0x1100
	s_cbranch_scc1 .Llru1_job
	v_readlane_b32 s36, v255, 11
	v_readlane_b32 s37, v255, 12
	v_readlane_b32 s38, v255, 13
	v_readlane_b32 s39, v255, 14
	v_readlane_b32 s40, v255, 15
	v_readlane_b32 s41, v255, 16
	v_readlane_b32 s42, v255, 17
	v_readlane_b32 s43, v255, 18
	v_readlane_b32 s44, v255, 19
	v_readlane_b32 s45, v255, 20
	v_readlane_b32 s46, v255, 21
	v_readlane_b32 s47, v255, 22
	v_readlane_b32 s48, v255, 23
	v_readlane_b32 s49, v255, 24
	v_readlane_b32 s50, v255, 25
	v_readlane_b32 s51, v255, 26
